# speedup vs baseline: 1.0068x; 1.0068x over previous
; template <int DH, int MODE>
; __device__ void attn_item(const Params& p, int layer, int b, int blk, int head, char* smem) {
;     ...
;     V_SCATTER_(vr0, 0);
;     V_SCATTER_(vr1, 1);
;     if (KCH > 2) {
;       V_SCATTER_(vr2, 2);
;       V_SCATTER_(vr3, 3);
;     }
;     KV_LOAD_(it + 1);
;     ...
;         const int qpos = blk * 128 + row;
;         const int kpb = ktok + half * 32;
;         float run = 0.f;
; #pragma unroll 2
;         for (int c = 7; c >= 0; --c) {
;           float4 v = s4[c];
;           float e[4] = {v.x, v.y, v.z, v.w};
; #pragma unroll
;           for (int k = 3; k >= 0; --k) {
;             float z = e[k];
;             bool valid = (kpb + c * 4 + k) < qpos;
;             float sp = fmaxf(z, 0.f) + __builtin_amdgcn_logf(1.f + __builtin_amdgcn_exp2f(-fabsf(z)));
;             run += valid ? -sp : 0.f;
;             e[k] = z + run;
;           }
;           s4[c] = make_float4(e[0], e[1], e[2], e[3]);
.LBB0_203:
	s_or_b64 exec, exec, s[50:51]
	s_add_i32 s26, s84, 1
	s_min_i32 s50, s26, s82
	s_sub_i32 s50, s82, s50
	s_lshl_b32 s50, s50, 6
	s_ashr_i32 s51, s50, 31
	s_add_u32 s50, s50, s81
	s_addc_u32 s51, s51, 0
	s_waitcnt lgkmcnt(0)
	s_barrier
	ds_write_b16 v171, v96
	ds_write_b16_d16_hi v171, v96 offset:64
	ds_write_b16 v171, v97 offset:128
	ds_write_b16_d16_hi v171, v97 offset:192
	ds_write_b16 v171, v98 offset:256
	ds_write_b16_d16_hi v171, v98 offset:320
	ds_write_b16 v171, v99 offset:384
	ds_write_b16_d16_hi v171, v99 offset:448
	ds_write_b16 v171, v100 offset:2048
	ds_write_b16_d16_hi v171, v100 offset:2112
	ds_write_b16 v171, v101 offset:2176
	ds_write_b16_d16_hi v171, v101 offset:2240
	ds_write_b16 v171, v102 offset:2304
	ds_write_b16_d16_hi v171, v102 offset:2368
	ds_write_b16 v171, v103 offset:2432
	ds_write_b16_d16_hi v171, v103 offset:2496
	s_waitcnt vmcnt(1)
	ds_write_b16 v171, v108 offset:4096
	ds_write_b16_d16_hi v171, v108 offset:4160
	ds_write_b16 v171, v109 offset:4224
	ds_write_b16_d16_hi v171, v109 offset:4288
	ds_write_b16 v171, v110 offset:4352
	ds_write_b16_d16_hi v171, v110 offset:4416
	ds_write_b16 v171, v111 offset:4480
	ds_write_b16_d16_hi v171, v111 offset:4544
	s_waitcnt vmcnt(0)
	ds_write_b16 v171, v104 offset:6144
	ds_write_b16_d16_hi v171, v104 offset:6208
	ds_write_b16 v171, v105 offset:6272
	ds_write_b16_d16_hi v171, v105 offset:6336
	ds_write_b16 v171, v106 offset:6400
	ds_write_b16_d16_hi v171, v106 offset:6464
	ds_write_b16 v171, v107 offset:6528
	ds_write_b16_d16_hi v171, v107 offset:6592
	v_lshl_add_u64 v[96:97], s[50:51], 0, v[134:135]
	v_mad_u64_u32 v[104:105], s[52:53], v96, s55, v[140:141]
	v_or_b32_e32 v96, s50, v132
	v_mad_i32_i24 v105, v97, s55, v105
	v_mad_u64_u32 v[106:107], s[52:53], v96, s55, v[142:143]
	v_add_co_u32_e32 v96, vcc, s69, v104
	v_mad_i32_i24 v107, s51, v160, v107
	s_nop 0
	v_addc_co_u32_e32 v97, vcc, 0, v105, vcc
	v_add_co_u32_e32 v98, vcc, 0x4c000, v104
	s_nop 1
	v_addc_co_u32_e32 v99, vcc, 0, v105, vcc
	v_add_co_u32_e32 v100, vcc, 0x72000, v104
	global_load_dwordx4 v[120:123], v[96:97], off
	global_load_dwordx4 v[116:119], v[98:99], off
	v_addc_co_u32_e32 v101, vcc, 0, v105, vcc
	global_load_dwordx4 v[96:99], v[106:107], off
	global_load_dwordx4 v[124:127], v[100:101], off
	s_nop 0
	global_load_dwordx4 v[100:103], v[106:107], off offset:64
	global_load_dwordx4 v[108:111], v[106:107], off offset:128
	global_load_dwordx4 v[112:115], v[104:105], off
	s_nop 0
	global_load_dwordx4 v[104:107], v[106:107], off offset:192
	s_and_saveexec_b64 s[50:51], s[8:9]
	s_cbranch_execz .LBB0_214
	v_mov_b32_e32 v146, 0
	s_mov_b32 s52, 0
	v_mov_b32_e32 v148, v166
	ds_read_b128 v[208:211], v167 offset:112
	ds_read_b128 v[204:207], v167 offset:96
	ds_read_b128 v[200:203], v167 offset:80
	ds_read_b128 v[196:199], v167 offset:64
	ds_read_b128 v[192:195], v167 offset:48
	ds_read_b128 v[188:191], v167 offset:32
	ds_read_b128 v[184:187], v167 offset:16
	ds_read_b128 v[180:183], v167
	v_sub_u32_e32 v212, v144, v173
	v_add_u32_e32 v212, 0xffffc040, v212
	s_waitcnt lgkmcnt(7)
	v_exp_f32_e64 v213, -|v211|
	v_exp_f32_e64 v214, -|v210|
	v_exp_f32_e64 v215, -|v209|
	v_max_f32_e32 v216, 0, v211
	v_max_f32_e32 v217, 0, v210
	v_max_f32_e32 v218, 0, v209
	v_add_f32_e32 v213, 1.0, v213
	v_add_f32_e32 v214, 1.0, v214
	v_add_f32_e32 v215, 1.0, v215
	v_log_f32_e32 v213, v213
	v_log_f32_e32 v214, v214
	v_log_f32_e32 v215, v215
	v_cmp_lt_i32_e32 vcc, 31, v212
	v_cmp_lt_i32_e64 s[92:93], 30, v212
	v_cmp_lt_i32_e64 s[94:95], 29, v212
	v_add_f32_e32 v213, v216, v213
	v_add_f32_e32 v214, v217, v214
	v_add_f32_e32 v215, v218, v215
	v_cndmask_b32_e64 v213, 0, -v213, vcc
	v_cndmask_b32_e64 v214, 0, -v214, s[92:93]
	v_cndmask_b32_e64 v215, 0, -v215, s[94:95]
	v_add_f32_e32 v146, v146, v213
	v_add_f32_e32 v211, v211, v146
	v_add_f32_e32 v146, v146, v214
	v_add_f32_e32 v210, v210, v146
	v_add_f32_e32 v146, v146, v215
	v_add_f32_e32 v209, v209, v146
	s_waitcnt lgkmcnt(6)
	v_exp_f32_e64 v213, -|v208|
	v_exp_f32_e64 v214, -|v207|
	v_exp_f32_e64 v215, -|v206|
	v_max_f32_e32 v216, 0, v208
	v_max_f32_e32 v217, 0, v207
	v_max_f32_e32 v218, 0, v206
	v_add_f32_e32 v213, 1.0, v213
	v_add_f32_e32 v214, 1.0, v214
	v_add_f32_e32 v215, 1.0, v215
	v_log_f32_e32 v213, v213
	v_log_f32_e32 v214, v214
	v_log_f32_e32 v215, v215
	v_cmp_lt_i32_e32 vcc, 28, v212
	v_cmp_lt_i32_e64 s[92:93], 27, v212
	v_cmp_lt_i32_e64 s[94:95], 26, v212
	v_add_f32_e32 v213, v216, v213
	v_add_f32_e32 v214, v217, v214
	v_add_f32_e32 v215, v218, v215
	v_cndmask_b32_e64 v213, 0, -v213, vcc
	v_cndmask_b32_e64 v214, 0, -v214, s[92:93]
	v_cndmask_b32_e64 v215, 0, -v215, s[94:95]
	v_add_f32_e32 v146, v146, v213
	v_add_f32_e32 v208, v208, v146
	v_add_f32_e32 v146, v146, v214
	v_add_f32_e32 v207, v207, v146
	v_add_f32_e32 v146, v146, v215
	v_add_f32_e32 v206, v206, v146
	s_waitcnt lgkmcnt(5)
; template <int DH, int MODE>
; __device__ void attn_item(const Params& p, int layer, int b, int blk, int head, char* smem) {
;     ...
;         for (int c = 7; c >= 0; --c) {
;           float4 v = s4[c];
;           float e[4] = {v.x, v.y, v.z, v.w};
; #pragma unroll
;           for (int k = 3; k >= 0; --k) {
;             float z = e[k];
;             bool valid = (kpb + c * 4 + k) < qpos;
;             float sp = fmaxf(z, 0.f) + __builtin_amdgcn_logf(1.f + __builtin_amdgcn_exp2f(-fabsf(z)));
;             run += valid ? -sp : 0.f;
;             e[k] = z + run;
;           }
;           s4[c] = make_float4(e[0], e[1], e[2], e[3]);
	v_exp_f32_e64 v213, -|v205|
	v_exp_f32_e64 v214, -|v204|
	v_exp_f32_e64 v215, -|v203|
	v_max_f32_e32 v216, 0, v205
	v_max_f32_e32 v217, 0, v204
	v_max_f32_e32 v218, 0, v203
	v_add_f32_e32 v213, 1.0, v213
	v_add_f32_e32 v214, 1.0, v214
	v_add_f32_e32 v215, 1.0, v215
	v_log_f32_e32 v213, v213
	v_log_f32_e32 v214, v214
	v_log_f32_e32 v215, v215
	v_cmp_lt_i32_e32 vcc, 25, v212
	v_cmp_lt_i32_e64 s[92:93], 24, v212
	v_cmp_lt_i32_e64 s[94:95], 23, v212
	v_add_f32_e32 v213, v216, v213
	v_add_f32_e32 v214, v217, v214
	v_add_f32_e32 v215, v218, v215
	v_cndmask_b32_e64 v213, 0, -v213, vcc
	v_cndmask_b32_e64 v214, 0, -v214, s[92:93]
	v_cndmask_b32_e64 v215, 0, -v215, s[94:95]
	v_add_f32_e32 v146, v146, v213
	v_add_f32_e32 v205, v205, v146
	v_add_f32_e32 v146, v146, v214
	v_add_f32_e32 v204, v204, v146
	v_add_f32_e32 v146, v146, v215
	v_add_f32_e32 v203, v203, v146
	v_exp_f32_e64 v213, -|v202|
	v_exp_f32_e64 v214, -|v201|
	v_exp_f32_e64 v215, -|v200|
	v_max_f32_e32 v216, 0, v202
	v_max_f32_e32 v217, 0, v201
	v_max_f32_e32 v218, 0, v200
	v_add_f32_e32 v213, 1.0, v213
	v_add_f32_e32 v214, 1.0, v214
	v_add_f32_e32 v215, 1.0, v215
	v_log_f32_e32 v213, v213
	v_log_f32_e32 v214, v214
	v_log_f32_e32 v215, v215
	v_cmp_lt_i32_e32 vcc, 22, v212
	v_cmp_lt_i32_e64 s[92:93], 21, v212
	v_cmp_lt_i32_e64 s[94:95], 20, v212
	v_add_f32_e32 v213, v216, v213
	v_add_f32_e32 v214, v217, v214
	v_add_f32_e32 v215, v218, v215
	v_cndmask_b32_e64 v213, 0, -v213, vcc
	v_cndmask_b32_e64 v214, 0, -v214, s[92:93]
	v_cndmask_b32_e64 v215, 0, -v215, s[94:95]
	v_add_f32_e32 v146, v146, v213
	v_add_f32_e32 v202, v202, v146
	v_add_f32_e32 v146, v146, v214
	v_add_f32_e32 v201, v201, v146
	v_add_f32_e32 v146, v146, v215
	v_add_f32_e32 v200, v200, v146
	s_waitcnt lgkmcnt(4)
	v_exp_f32_e64 v213, -|v199|
	v_exp_f32_e64 v214, -|v198|
	v_exp_f32_e64 v215, -|v197|
	v_max_f32_e32 v216, 0, v199
	v_max_f32_e32 v217, 0, v198
	v_max_f32_e32 v218, 0, v197
	v_add_f32_e32 v213, 1.0, v213
	v_add_f32_e32 v214, 1.0, v214
	v_add_f32_e32 v215, 1.0, v215
	v_log_f32_e32 v213, v213
	v_log_f32_e32 v214, v214
	v_log_f32_e32 v215, v215
	v_cmp_lt_i32_e32 vcc, 19, v212
	v_cmp_lt_i32_e64 s[92:93], 18, v212
	v_cmp_lt_i32_e64 s[94:95], 17, v212
	v_add_f32_e32 v213, v216, v213
	v_add_f32_e32 v214, v217, v214
	v_add_f32_e32 v215, v218, v215
	v_cndmask_b32_e64 v213, 0, -v213, vcc
	v_cndmask_b32_e64 v214, 0, -v214, s[92:93]
	v_cndmask_b32_e64 v215, 0, -v215, s[94:95]
	v_add_f32_e32 v146, v146, v213
	v_add_f32_e32 v199, v199, v146
	v_add_f32_e32 v146, v146, v214
	v_add_f32_e32 v198, v198, v146
	v_add_f32_e32 v146, v146, v215
	v_add_f32_e32 v197, v197, v146
	s_waitcnt lgkmcnt(3)
	v_exp_f32_e64 v213, -|v196|
	v_exp_f32_e64 v214, -|v195|
	v_exp_f32_e64 v215, -|v194|
	v_max_f32_e32 v216, 0, v196
	v_max_f32_e32 v217, 0, v195
	v_max_f32_e32 v218, 0, v194
	v_add_f32_e32 v213, 1.0, v213
	v_add_f32_e32 v214, 1.0, v214
	v_add_f32_e32 v215, 1.0, v215
	v_log_f32_e32 v213, v213
	v_log_f32_e32 v214, v214
	v_log_f32_e32 v215, v215
	v_cmp_lt_i32_e32 vcc, 16, v212
	v_cmp_lt_i32_e64 s[92:93], 15, v212
	v_cmp_lt_i32_e64 s[94:95], 14, v212
	v_add_f32_e32 v213, v216, v213
	v_add_f32_e32 v214, v217, v214
	v_add_f32_e32 v215, v218, v215
	v_cndmask_b32_e64 v213, 0, -v213, vcc
	v_cndmask_b32_e64 v214, 0, -v214, s[92:93]
	v_cndmask_b32_e64 v215, 0, -v215, s[94:95]
	v_add_f32_e32 v146, v146, v213
	v_add_f32_e32 v196, v196, v146
	v_add_f32_e32 v146, v146, v214
	v_add_f32_e32 v195, v195, v146
	v_add_f32_e32 v146, v146, v215
	v_add_f32_e32 v194, v194, v146
	s_waitcnt lgkmcnt(2)
	v_exp_f32_e64 v213, -|v193|
	v_exp_f32_e64 v214, -|v192|
	v_exp_f32_e64 v215, -|v191|
	v_max_f32_e32 v216, 0, v193
	v_max_f32_e32 v217, 0, v192
	v_max_f32_e32 v218, 0, v191
	v_add_f32_e32 v213, 1.0, v213
	v_add_f32_e32 v214, 1.0, v214
	v_add_f32_e32 v215, 1.0, v215
	v_log_f32_e32 v213, v213
	v_log_f32_e32 v214, v214
	v_log_f32_e32 v215, v215
	v_cmp_lt_i32_e32 vcc, 13, v212
	v_cmp_lt_i32_e64 s[92:93], 12, v212
	v_cmp_lt_i32_e64 s[94:95], 11, v212
	v_add_f32_e32 v213, v216, v213
	v_add_f32_e32 v214, v217, v214
	v_add_f32_e32 v215, v218, v215
	v_cndmask_b32_e64 v213, 0, -v213, vcc
	v_cndmask_b32_e64 v214, 0, -v214, s[92:93]
	v_cndmask_b32_e64 v215, 0, -v215, s[94:95]
	v_add_f32_e32 v146, v146, v213
	v_add_f32_e32 v193, v193, v146
	v_add_f32_e32 v146, v146, v214
	v_add_f32_e32 v192, v192, v146
	v_add_f32_e32 v146, v146, v215
	v_add_f32_e32 v191, v191, v146
	v_exp_f32_e64 v213, -|v190|
	v_exp_f32_e64 v214, -|v189|
	v_exp_f32_e64 v215, -|v188|
	v_max_f32_e32 v216, 0, v190
	v_max_f32_e32 v217, 0, v189
	v_max_f32_e32 v218, 0, v188
	v_add_f32_e32 v213, 1.0, v213
	v_add_f32_e32 v214, 1.0, v214
	v_add_f32_e32 v215, 1.0, v215
	v_log_f32_e32 v213, v213
	v_log_f32_e32 v214, v214
	v_log_f32_e32 v215, v215
	v_cmp_lt_i32_e32 vcc, 10, v212
	v_cmp_lt_i32_e64 s[92:93], 9, v212
	v_cmp_lt_i32_e64 s[94:95], 8, v212
	v_add_f32_e32 v213, v216, v213
	v_add_f32_e32 v214, v217, v214
	v_add_f32_e32 v215, v218, v215
	v_cndmask_b32_e64 v213, 0, -v213, vcc
	v_cndmask_b32_e64 v214, 0, -v214, s[92:93]
	v_cndmask_b32_e64 v215, 0, -v215, s[94:95]
	v_add_f32_e32 v146, v146, v213
	v_add_f32_e32 v190, v190, v146
	v_add_f32_e32 v146, v146, v214
	v_add_f32_e32 v189, v189, v146
	v_add_f32_e32 v146, v146, v215
	v_add_f32_e32 v188, v188, v146
	s_waitcnt lgkmcnt(1)
; __device__ __forceinline__ unsigned pack2(float a, float b) { return (unsigned)f2bf(a) | ((unsigned)f2bf(b) << 16); }
; template <int DH, int MODE>
; __device__ void attn_item(const Params& p, int layer, int b, int blk, int head, char* smem) {
;     ...
;         for (int c = 7; c >= 0; --c) {
;           float4 v = s4[c];
;           float e[4] = {v.x, v.y, v.z, v.w};
; #pragma unroll
;           for (int k = 3; k >= 0; --k) {
;             float z = e[k];
;             bool valid = (kpb + c * 4 + k) < qpos;
;             float sp = fmaxf(z, 0.f) + __builtin_amdgcn_logf(1.f + __builtin_amdgcn_exp2f(-fabsf(z)));
;             run += valid ? -sp : 0.f;
;             e[k] = z + run;
;           }
;           s4[c] = make_float4(e[0], e[1], e[2], e[3]);
;         }
;         float other = __shfl_xor(run, 1);
;         float offs = m_run + (half == 0 ? other : 0.f);
; #pragma unroll 2
;         for (int s8 = 0; s8 < 4; ++s8) {
;           float4 va = s4[2 * s8], vb = s4[2 * s8 + 1];
;           float e[8] = {va.x, va.y, va.z, va.w, vb.x, vb.y, vb.z, vb.w};
;           float pv[8];
; #pragma unroll
;           for (int k = 0; k < 8; ++k) {
;             bool valid = (kpb + s8 * 8 + k) < qpos;
;             pv[k] = valid ? __builtin_amdgcn_exp2f(e[k] + offs) : 0.f;
;           }
;           uint4 ov;
;           ov.x = pack2(pv[0], pv[1]); ov.y = pack2(pv[2], pv[3]);
;           ov.z = pack2(pv[4], pv[5]); ov.w = pack2(pv[6], pv[7]);
	v_exp_f32_e64 v213, -|v187|
	v_exp_f32_e64 v214, -|v186|
	v_exp_f32_e64 v215, -|v185|
	v_max_f32_e32 v216, 0, v187
	v_max_f32_e32 v217, 0, v186
	v_max_f32_e32 v218, 0, v185
	v_add_f32_e32 v213, 1.0, v213
	v_add_f32_e32 v214, 1.0, v214
	v_add_f32_e32 v215, 1.0, v215
	v_log_f32_e32 v213, v213
	v_log_f32_e32 v214, v214
	v_log_f32_e32 v215, v215
	v_cmp_lt_i32_e32 vcc, 7, v212
	v_cmp_lt_i32_e64 s[92:93], 6, v212
	v_cmp_lt_i32_e64 s[94:95], 5, v212
	v_add_f32_e32 v213, v216, v213
	v_add_f32_e32 v214, v217, v214
	v_add_f32_e32 v215, v218, v215
	v_cndmask_b32_e64 v213, 0, -v213, vcc
	v_cndmask_b32_e64 v214, 0, -v214, s[92:93]
	v_cndmask_b32_e64 v215, 0, -v215, s[94:95]
	v_add_f32_e32 v146, v146, v213
	v_add_f32_e32 v187, v187, v146
	v_add_f32_e32 v146, v146, v214
	v_add_f32_e32 v186, v186, v146
	v_add_f32_e32 v146, v146, v215
	v_add_f32_e32 v185, v185, v146
	s_waitcnt lgkmcnt(0)
	v_exp_f32_e64 v213, -|v184|
	v_exp_f32_e64 v214, -|v183|
	v_exp_f32_e64 v215, -|v182|
	v_max_f32_e32 v216, 0, v184
	v_max_f32_e32 v217, 0, v183
	v_max_f32_e32 v218, 0, v182
	v_add_f32_e32 v213, 1.0, v213
	v_add_f32_e32 v214, 1.0, v214
	v_add_f32_e32 v215, 1.0, v215
	v_log_f32_e32 v213, v213
	v_log_f32_e32 v214, v214
	v_log_f32_e32 v215, v215
	v_cmp_lt_i32_e32 vcc, 4, v212
	v_cmp_lt_i32_e64 s[92:93], 3, v212
	v_cmp_lt_i32_e64 s[94:95], 2, v212
	v_add_f32_e32 v213, v216, v213
	v_add_f32_e32 v214, v217, v214
	v_add_f32_e32 v215, v218, v215
	v_cndmask_b32_e64 v213, 0, -v213, vcc
	v_cndmask_b32_e64 v214, 0, -v214, s[92:93]
	v_cndmask_b32_e64 v215, 0, -v215, s[94:95]
	v_add_f32_e32 v146, v146, v213
	v_add_f32_e32 v184, v184, v146
	v_add_f32_e32 v146, v146, v214
	v_add_f32_e32 v183, v183, v146
	v_add_f32_e32 v146, v146, v215
	v_add_f32_e32 v182, v182, v146
	v_exp_f32_e64 v213, -|v181|
	v_exp_f32_e64 v214, -|v180|
	v_max_f32_e32 v216, 0, v181
	v_max_f32_e32 v217, 0, v180
	v_add_f32_e32 v213, 1.0, v213
	v_add_f32_e32 v214, 1.0, v214
	v_log_f32_e32 v213, v213
	v_log_f32_e32 v214, v214
	v_cmp_lt_i32_e32 vcc, 1, v212
	v_cmp_lt_i32_e64 s[92:93], 0, v212
	s_nop 0
	v_add_f32_e32 v213, v216, v213
	v_add_f32_e32 v214, v217, v214
	v_cndmask_b32_e64 v213, 0, -v213, vcc
	v_cndmask_b32_e64 v214, 0, -v214, s[92:93]
	v_add_f32_e32 v146, v146, v213
	v_add_f32_e32 v181, v181, v146
	v_add_f32_e32 v146, v146, v214
	v_add_f32_e32 v180, v180, v146
	ds_write_b128 v167, v[180:183]
	ds_write_b128 v167, v[184:187] offset:16
	ds_write_b128 v167, v[188:191] offset:32
	ds_write_b128 v167, v[192:195] offset:48
	ds_write_b128 v167, v[196:199] offset:64
	ds_write_b128 v167, v[200:203] offset:80
	ds_write_b128 v167, v[204:207] offset:96
	ds_write_b128 v167, v[208:211] offset:112
	ds_bpermute_b32 v147, v163, v146
	s_mov_b32 s85, 0
	v_mov_b32_e32 v175, v168
	v_mov_b32_e32 v177, v167
	s_waitcnt lgkmcnt(0)
	v_cndmask_b32_e64 v148, 0, v147, s[6:7]
	v_add_f32_e32 v176, v174, v148
	ds_read_b128 v[180:183], v177
	ds_read_b128 v[184:187], v177 offset:16
	ds_read_b128 v[188:191], v177 offset:32
	ds_read_b128 v[192:195], v177 offset:48
	ds_read_b128 v[196:199], v177 offset:64
	ds_read_b128 v[200:203], v177 offset:80
	ds_read_b128 v[204:207], v177 offset:96
	ds_read_b128 v[208:211], v177 offset:112
	v_sub_u32_e32 v212, v144, v173
	v_add_u32_e32 v212, 0xffffc040, v212
	s_waitcnt lgkmcnt(7)
	v_add_f32_e32 v180, v176, v180
	v_add_f32_e32 v181, v176, v181
	v_add_f32_e32 v182, v176, v182
	v_exp_f32_e32 v180, v180
	v_exp_f32_e32 v181, v181
	v_exp_f32_e32 v182, v182
	v_cmp_lt_i32_e32 vcc, 0, v212
	v_cmp_lt_i32_e64 s[92:93], 1, v212
	v_cmp_lt_i32_e64 s[94:95], 2, v212
	v_cndmask_b32_e32 v180, 0, v180, vcc
	v_cndmask_b32_e64 v181, 0, v181, s[92:93]
	v_cndmask_b32_e64 v182, 0, v182, s[94:95]
	s_waitcnt lgkmcnt(6)
	v_add_f32_e32 v183, v176, v183
	v_add_f32_e32 v184, v176, v184
	v_add_f32_e32 v185, v176, v185
	v_exp_f32_e32 v183, v183
	v_exp_f32_e32 v184, v184
	v_exp_f32_e32 v185, v185
	v_cmp_lt_i32_e32 vcc, 3, v212
	v_cmp_lt_i32_e64 s[92:93], 4, v212
	v_cmp_lt_i32_e64 s[94:95], 5, v212
	v_cndmask_b32_e32 v183, 0, v183, vcc
	v_cndmask_b32_e64 v184, 0, v184, s[92:93]
	v_cndmask_b32_e64 v185, 0, v185, s[94:95]
	s_waitcnt lgkmcnt(5)
; __device__ __forceinline__ unsigned pack2(float a, float b) { return (unsigned)f2bf(a) | ((unsigned)f2bf(b) << 16); }
; template <int DH, int MODE>
; __device__ void attn_item(const Params& p, int layer, int b, int blk, int head, char* smem) {
;     ...
; #pragma unroll 2
;         for (int s8 = 0; s8 < 4; ++s8) {
;           float4 va = s4[2 * s8], vb = s4[2 * s8 + 1];
;           float e[8] = {va.x, va.y, va.z, va.w, vb.x, vb.y, vb.z, vb.w};
;           float pv[8];
; #pragma unroll
;           for (int k = 0; k < 8; ++k) {
;             bool valid = (kpb + s8 * 8 + k) < qpos;
;             pv[k] = valid ? __builtin_amdgcn_exp2f(e[k] + offs) : 0.f;
;           }
;           uint4 ov;
;           ov.x = pack2(pv[0], pv[1]); ov.y = pack2(pv[2], pv[3]);
;           ov.z = pack2(pv[4], pv[5]); ov.w = pack2(pv[6], pv[7]);
;           *reinterpret_cast<uint4*>(prow + s8 * 16) = ov;
;         }
	v_add_f32_e32 v186, v176, v186
	v_add_f32_e32 v187, v176, v187
	v_add_f32_e32 v188, v176, v188
	v_exp_f32_e32 v186, v186
	v_exp_f32_e32 v187, v187
	v_exp_f32_e32 v188, v188
	v_cmp_lt_i32_e32 vcc, 6, v212
	v_cmp_lt_i32_e64 s[92:93], 7, v212
	v_cmp_lt_i32_e64 s[94:95], 8, v212
	v_cndmask_b32_e32 v186, 0, v186, vcc
	v_cndmask_b32_e64 v187, 0, v187, s[92:93]
	v_cndmask_b32_e64 v188, 0, v188, s[94:95]
	v_add_f32_e32 v189, v176, v189
	v_add_f32_e32 v190, v176, v190
	v_add_f32_e32 v191, v176, v191
	v_exp_f32_e32 v189, v189
	v_exp_f32_e32 v190, v190
	v_exp_f32_e32 v191, v191
	v_cmp_lt_i32_e32 vcc, 9, v212
	v_cmp_lt_i32_e64 s[92:93], 10, v212
	v_cmp_lt_i32_e64 s[94:95], 11, v212
	v_cndmask_b32_e32 v189, 0, v189, vcc
	v_cndmask_b32_e64 v190, 0, v190, s[92:93]
	v_cndmask_b32_e64 v191, 0, v191, s[94:95]
	s_waitcnt lgkmcnt(4)
	v_add_f32_e32 v192, v176, v192
	v_add_f32_e32 v193, v176, v193
	v_add_f32_e32 v194, v176, v194
	v_exp_f32_e32 v192, v192
	v_exp_f32_e32 v193, v193
	v_exp_f32_e32 v194, v194
	v_cmp_lt_i32_e32 vcc, 12, v212
	v_cmp_lt_i32_e64 s[92:93], 13, v212
	v_cmp_lt_i32_e64 s[94:95], 14, v212
	v_cndmask_b32_e32 v192, 0, v192, vcc
	v_cndmask_b32_e64 v193, 0, v193, s[92:93]
	v_cndmask_b32_e64 v194, 0, v194, s[94:95]
	s_waitcnt lgkmcnt(3)
	v_add_f32_e32 v195, v176, v195
	v_add_f32_e32 v196, v176, v196
	v_add_f32_e32 v197, v176, v197
	v_exp_f32_e32 v195, v195
	v_exp_f32_e32 v196, v196
	v_exp_f32_e32 v197, v197
	v_cmp_lt_i32_e32 vcc, 15, v212
	v_cmp_lt_i32_e64 s[92:93], 16, v212
	v_cmp_lt_i32_e64 s[94:95], 17, v212
	v_cndmask_b32_e32 v195, 0, v195, vcc
	v_cndmask_b32_e64 v196, 0, v196, s[92:93]
	v_cndmask_b32_e64 v197, 0, v197, s[94:95]
	s_waitcnt lgkmcnt(2)
	v_add_f32_e32 v198, v176, v198
	v_add_f32_e32 v199, v176, v199
	v_add_f32_e32 v200, v176, v200
	v_exp_f32_e32 v198, v198
	v_exp_f32_e32 v199, v199
	v_exp_f32_e32 v200, v200
	v_cmp_lt_i32_e32 vcc, 18, v212
	v_cmp_lt_i32_e64 s[92:93], 19, v212
	v_cmp_lt_i32_e64 s[94:95], 20, v212
	v_cndmask_b32_e32 v198, 0, v198, vcc
	v_cndmask_b32_e64 v199, 0, v199, s[92:93]
	v_cndmask_b32_e64 v200, 0, v200, s[94:95]
	v_add_f32_e32 v201, v176, v201
	v_add_f32_e32 v202, v176, v202
	v_add_f32_e32 v203, v176, v203
	v_exp_f32_e32 v201, v201
	v_exp_f32_e32 v202, v202
	v_exp_f32_e32 v203, v203
	v_cmp_lt_i32_e32 vcc, 21, v212
	v_cmp_lt_i32_e64 s[92:93], 22, v212
	v_cmp_lt_i32_e64 s[94:95], 23, v212
	v_cndmask_b32_e32 v201, 0, v201, vcc
	v_cndmask_b32_e64 v202, 0, v202, s[92:93]
	v_cndmask_b32_e64 v203, 0, v203, s[94:95]
	s_waitcnt lgkmcnt(1)
	v_add_f32_e32 v204, v176, v204
	v_add_f32_e32 v205, v176, v205
	v_add_f32_e32 v206, v176, v206
	v_exp_f32_e32 v204, v204
	v_exp_f32_e32 v205, v205
	v_exp_f32_e32 v206, v206
	v_cmp_lt_i32_e32 vcc, 24, v212
	v_cmp_lt_i32_e64 s[92:93], 25, v212
	v_cmp_lt_i32_e64 s[94:95], 26, v212
	v_cndmask_b32_e32 v204, 0, v204, vcc
	v_cndmask_b32_e64 v205, 0, v205, s[92:93]
	v_cndmask_b32_e64 v206, 0, v206, s[94:95]
	s_waitcnt lgkmcnt(0)
	v_add_f32_e32 v207, v176, v207
	v_add_f32_e32 v208, v176, v208
	v_add_f32_e32 v209, v176, v209
	v_exp_f32_e32 v207, v207
	v_exp_f32_e32 v208, v208
	v_exp_f32_e32 v209, v209
	v_cmp_lt_i32_e32 vcc, 27, v212
	v_cmp_lt_i32_e64 s[92:93], 28, v212
	v_cmp_lt_i32_e64 s[94:95], 29, v212
	v_cndmask_b32_e32 v207, 0, v207, vcc
	v_cndmask_b32_e64 v208, 0, v208, s[92:93]
	v_cndmask_b32_e64 v209, 0, v209, s[94:95]
	v_add_f32_e32 v210, v176, v210
	v_add_f32_e32 v211, v176, v211
	v_exp_f32_e32 v210, v210
	v_exp_f32_e32 v211, v211
	v_cmp_lt_i32_e32 vcc, 30, v212
	v_cmp_lt_i32_e64 s[92:93], 31, v212
	s_nop 0
	v_cndmask_b32_e32 v210, 0, v210, vcc
	v_cndmask_b32_e64 v211, 0, v211, s[92:93]
	v_cvt_pk_bf16_f32 v148, v180, v181
	v_cvt_pk_bf16_f32 v149, v182, v183
	v_cvt_pk_bf16_f32 v150, v184, v185
	v_cvt_pk_bf16_f32 v151, v186, v187
	ds_write_b128 v175, v[148:151]
	s_nop 0
	v_cvt_pk_bf16_f32 v148, v188, v189
	v_cvt_pk_bf16_f32 v149, v190, v191
	v_cvt_pk_bf16_f32 v150, v192, v193
	v_cvt_pk_bf16_f32 v151, v194, v195
	ds_write_b128 v175, v[148:151] offset:16
	s_nop 0
	v_cvt_pk_bf16_f32 v148, v196, v197
	v_cvt_pk_bf16_f32 v149, v198, v199
	v_cvt_pk_bf16_f32 v150, v200, v201
	v_cvt_pk_bf16_f32 v151, v202, v203
	ds_write_b128 v175, v[148:151] offset:32
	s_nop 0
	v_cvt_pk_bf16_f32 v148, v204, v205
	v_cvt_pk_bf16_f32 v149, v206, v207
	v_cvt_pk_bf16_f32 v150, v208, v209
	v_cvt_pk_bf16_f32 v151, v210, v211
	ds_write_b128 v175, v[148:151] offset:48
	s_branch .LBB0_213

; template <int DH, int MODE>
; __device__ void attn_item(const Params& p, int layer, int b, int blk, int head, char* smem) {
;     ...
;     V_SCATTER_(vr0, 0);
;     V_SCATTER_(vr1, 1);
;     if (KCH > 2) {
;       V_SCATTER_(vr2, 2);
;       V_SCATTER_(vr3, 3);
;     }
;     KV_LOAD_(it + 1);
;     ...
;         const int qpos = blk * 128 + row;
;         const int kpb = ktok + half * 32;
;         float run = 0.f;
; #pragma unroll 2
;         for (int c = 7; c >= 0; --c) {
;           float4 v = s4[c];
;           float e[4] = {v.x, v.y, v.z, v.w};
; #pragma unroll
;           for (int k = 3; k >= 0; --k) {
;             float z = e[k];
;             bool valid = (kpb + c * 4 + k) < qpos;
;             float sp = fmaxf(z, 0.f) + __builtin_amdgcn_logf(1.f + __builtin_amdgcn_exp2f(-fabsf(z)));
;             run += valid ? -sp : 0.f;
;             e[k] = z + run;
;           }
;           s4[c] = make_float4(e[0], e[1], e[2], e[3]);
.LBB0_524:
	s_or_b64 exec, exec, s[52:53]
	s_add_i32 s36, s87, 1
	s_min_i32 s52, s36, s85
	s_sub_i32 s52, s85, s52
	s_lshl_b32 s52, s52, 6
	s_ashr_i32 s53, s52, 31
	s_add_u32 s52, s52, s84
	s_addc_u32 s53, s53, 0
	s_waitcnt lgkmcnt(0)
	s_barrier
	ds_write_b16 v171, v96
	ds_write_b16_d16_hi v171, v96 offset:64
	ds_write_b16 v171, v97 offset:128
	ds_write_b16_d16_hi v171, v97 offset:192
	ds_write_b16 v171, v98 offset:256
	ds_write_b16_d16_hi v171, v98 offset:320
	ds_write_b16 v171, v99 offset:384
	ds_write_b16_d16_hi v171, v99 offset:448
	ds_write_b16 v171, v100 offset:2048
	ds_write_b16_d16_hi v171, v100 offset:2112
	ds_write_b16 v171, v101 offset:2176
	ds_write_b16_d16_hi v171, v101 offset:2240
	ds_write_b16 v171, v102 offset:2304
	ds_write_b16_d16_hi v171, v102 offset:2368
	ds_write_b16 v171, v103 offset:2432
	ds_write_b16_d16_hi v171, v103 offset:2496
	s_waitcnt vmcnt(1)
	ds_write_b16 v171, v108 offset:4096
	ds_write_b16_d16_hi v171, v108 offset:4160
	ds_write_b16 v171, v109 offset:4224
	ds_write_b16_d16_hi v171, v109 offset:4288
	ds_write_b16 v171, v110 offset:4352
	ds_write_b16_d16_hi v171, v110 offset:4416
	ds_write_b16 v171, v111 offset:4480
	ds_write_b16_d16_hi v171, v111 offset:4544
	s_waitcnt vmcnt(0)
	ds_write_b16 v171, v104 offset:6144
	ds_write_b16_d16_hi v171, v104 offset:6208
	ds_write_b16 v171, v105 offset:6272
	ds_write_b16_d16_hi v171, v105 offset:6336
	ds_write_b16 v171, v106 offset:6400
	ds_write_b16_d16_hi v171, v106 offset:6464
	ds_write_b16 v171, v107 offset:6528
	ds_write_b16_d16_hi v171, v107 offset:6592
	v_lshl_add_u64 v[96:97], s[52:53], 0, v[134:135]
	v_mad_u64_u32 v[104:105], s[54:55], v96, s63, v[140:141]
	v_or_b32_e32 v96, s52, v132
	v_mad_i32_i24 v105, v97, s63, v105
	v_mad_u64_u32 v[106:107], s[54:55], v96, s63, v[142:143]
	v_add_co_u32_e32 v96, vcc, s71, v104
	v_mad_i32_i24 v107, s53, v160, v107
	s_nop 0
	v_addc_co_u32_e32 v97, vcc, 0, v105, vcc
	v_add_co_u32_e32 v98, vcc, 0x4c000, v104
	s_nop 1
	v_addc_co_u32_e32 v99, vcc, 0, v105, vcc
	v_add_co_u32_e32 v100, vcc, 0x72000, v104
	global_load_dwordx4 v[120:123], v[96:97], off
	global_load_dwordx4 v[116:119], v[98:99], off
	v_addc_co_u32_e32 v101, vcc, 0, v105, vcc
	global_load_dwordx4 v[96:99], v[106:107], off
	global_load_dwordx4 v[124:127], v[100:101], off
	s_nop 0
	global_load_dwordx4 v[100:103], v[106:107], off offset:64
	global_load_dwordx4 v[108:111], v[106:107], off offset:128
	global_load_dwordx4 v[112:115], v[104:105], off
	s_nop 0
	global_load_dwordx4 v[104:107], v[106:107], off offset:192
	s_and_saveexec_b64 s[52:53], s[16:17]
	s_cbranch_execz .LBB0_535
	v_mov_b32_e32 v146, 0
	s_mov_b32 s54, 0
	v_mov_b32_e32 v148, v166
	ds_read_b128 v[208:211], v167 offset:112
	ds_read_b128 v[204:207], v167 offset:96
	ds_read_b128 v[200:203], v167 offset:80
	ds_read_b128 v[196:199], v167 offset:64
	ds_read_b128 v[192:195], v167 offset:48
	ds_read_b128 v[188:191], v167 offset:32
	ds_read_b128 v[184:187], v167 offset:16
	ds_read_b128 v[180:183], v167
	v_sub_u32_e32 v212, v144, v173
	v_add_u32_e32 v212, 0xffffc040, v212
	s_waitcnt lgkmcnt(7)
	v_exp_f32_e64 v213, -|v211|
	v_exp_f32_e64 v214, -|v210|
	v_exp_f32_e64 v215, -|v209|
	v_max_f32_e32 v216, 0, v211
	v_max_f32_e32 v217, 0, v210
	v_max_f32_e32 v218, 0, v209
	v_add_f32_e32 v213, 1.0, v213
	v_add_f32_e32 v214, 1.0, v214
	v_add_f32_e32 v215, 1.0, v215
	v_log_f32_e32 v213, v213
	v_log_f32_e32 v214, v214
	v_log_f32_e32 v215, v215
	v_cmp_lt_i32_e32 vcc, 31, v212
	v_cmp_lt_i32_e64 s[92:93], 30, v212
	v_cmp_lt_i32_e64 s[94:95], 29, v212
	v_add_f32_e32 v213, v216, v213
	v_add_f32_e32 v214, v217, v214
	v_add_f32_e32 v215, v218, v215
	v_cndmask_b32_e64 v213, 0, -v213, vcc
	v_cndmask_b32_e64 v214, 0, -v214, s[92:93]
	v_cndmask_b32_e64 v215, 0, -v215, s[94:95]
	v_add_f32_e32 v146, v146, v213
	v_add_f32_e32 v211, v211, v146
	v_add_f32_e32 v146, v146, v214
	v_add_f32_e32 v210, v210, v146
	v_add_f32_e32 v146, v146, v215
	v_add_f32_e32 v209, v209, v146
	s_waitcnt lgkmcnt(6)
	v_exp_f32_e64 v213, -|v208|
	v_exp_f32_e64 v214, -|v207|
	v_exp_f32_e64 v215, -|v206|
	v_max_f32_e32 v216, 0, v208
	v_max_f32_e32 v217, 0, v207
	v_max_f32_e32 v218, 0, v206
	v_add_f32_e32 v213, 1.0, v213
	v_add_f32_e32 v214, 1.0, v214
	v_add_f32_e32 v215, 1.0, v215
	v_log_f32_e32 v213, v213
	v_log_f32_e32 v214, v214
	v_log_f32_e32 v215, v215
	v_cmp_lt_i32_e32 vcc, 28, v212
	v_cmp_lt_i32_e64 s[92:93], 27, v212
	v_cmp_lt_i32_e64 s[94:95], 26, v212
	v_add_f32_e32 v213, v216, v213
	v_add_f32_e32 v214, v217, v214
	v_add_f32_e32 v215, v218, v215
	v_cndmask_b32_e64 v213, 0, -v213, vcc
	v_cndmask_b32_e64 v214, 0, -v214, s[92:93]
	v_cndmask_b32_e64 v215, 0, -v215, s[94:95]
	v_add_f32_e32 v146, v146, v213
	v_add_f32_e32 v208, v208, v146
	v_add_f32_e32 v146, v146, v214
	v_add_f32_e32 v207, v207, v146
	v_add_f32_e32 v146, v146, v215
	v_add_f32_e32 v206, v206, v146
	s_waitcnt lgkmcnt(5)
; template <int DH, int MODE>
; __device__ void attn_item(const Params& p, int layer, int b, int blk, int head, char* smem) {
;     ...
;         for (int c = 7; c >= 0; --c) {
;           float4 v = s4[c];
;           float e[4] = {v.x, v.y, v.z, v.w};
; #pragma unroll
;           for (int k = 3; k >= 0; --k) {
;             float z = e[k];
;             bool valid = (kpb + c * 4 + k) < qpos;
;             float sp = fmaxf(z, 0.f) + __builtin_amdgcn_logf(1.f + __builtin_amdgcn_exp2f(-fabsf(z)));
;             run += valid ? -sp : 0.f;
;             e[k] = z + run;
;           }
;           s4[c] = make_float4(e[0], e[1], e[2], e[3]);
	v_exp_f32_e64 v213, -|v205|
	v_exp_f32_e64 v214, -|v204|
	v_exp_f32_e64 v215, -|v203|
	v_max_f32_e32 v216, 0, v205
	v_max_f32_e32 v217, 0, v204
	v_max_f32_e32 v218, 0, v203
	v_add_f32_e32 v213, 1.0, v213
	v_add_f32_e32 v214, 1.0, v214
	v_add_f32_e32 v215, 1.0, v215
	v_log_f32_e32 v213, v213
	v_log_f32_e32 v214, v214
	v_log_f32_e32 v215, v215
	v_cmp_lt_i32_e32 vcc, 25, v212
	v_cmp_lt_i32_e64 s[92:93], 24, v212
	v_cmp_lt_i32_e64 s[94:95], 23, v212
	v_add_f32_e32 v213, v216, v213
	v_add_f32_e32 v214, v217, v214
	v_add_f32_e32 v215, v218, v215
	v_cndmask_b32_e64 v213, 0, -v213, vcc
	v_cndmask_b32_e64 v214, 0, -v214, s[92:93]
	v_cndmask_b32_e64 v215, 0, -v215, s[94:95]
	v_add_f32_e32 v146, v146, v213
	v_add_f32_e32 v205, v205, v146
	v_add_f32_e32 v146, v146, v214
	v_add_f32_e32 v204, v204, v146
	v_add_f32_e32 v146, v146, v215
	v_add_f32_e32 v203, v203, v146
	v_exp_f32_e64 v213, -|v202|
	v_exp_f32_e64 v214, -|v201|
	v_exp_f32_e64 v215, -|v200|
	v_max_f32_e32 v216, 0, v202
	v_max_f32_e32 v217, 0, v201
	v_max_f32_e32 v218, 0, v200
	v_add_f32_e32 v213, 1.0, v213
	v_add_f32_e32 v214, 1.0, v214
	v_add_f32_e32 v215, 1.0, v215
	v_log_f32_e32 v213, v213
	v_log_f32_e32 v214, v214
	v_log_f32_e32 v215, v215
	v_cmp_lt_i32_e32 vcc, 22, v212
	v_cmp_lt_i32_e64 s[92:93], 21, v212
	v_cmp_lt_i32_e64 s[94:95], 20, v212
	v_add_f32_e32 v213, v216, v213
	v_add_f32_e32 v214, v217, v214
	v_add_f32_e32 v215, v218, v215
	v_cndmask_b32_e64 v213, 0, -v213, vcc
	v_cndmask_b32_e64 v214, 0, -v214, s[92:93]
	v_cndmask_b32_e64 v215, 0, -v215, s[94:95]
	v_add_f32_e32 v146, v146, v213
	v_add_f32_e32 v202, v202, v146
	v_add_f32_e32 v146, v146, v214
	v_add_f32_e32 v201, v201, v146
	v_add_f32_e32 v146, v146, v215
	v_add_f32_e32 v200, v200, v146
	s_waitcnt lgkmcnt(4)
	v_exp_f32_e64 v213, -|v199|
	v_exp_f32_e64 v214, -|v198|
	v_exp_f32_e64 v215, -|v197|
	v_max_f32_e32 v216, 0, v199
	v_max_f32_e32 v217, 0, v198
	v_max_f32_e32 v218, 0, v197
	v_add_f32_e32 v213, 1.0, v213
	v_add_f32_e32 v214, 1.0, v214
	v_add_f32_e32 v215, 1.0, v215
	v_log_f32_e32 v213, v213
	v_log_f32_e32 v214, v214
	v_log_f32_e32 v215, v215
	v_cmp_lt_i32_e32 vcc, 19, v212
	v_cmp_lt_i32_e64 s[92:93], 18, v212
	v_cmp_lt_i32_e64 s[94:95], 17, v212
	v_add_f32_e32 v213, v216, v213
	v_add_f32_e32 v214, v217, v214
	v_add_f32_e32 v215, v218, v215
	v_cndmask_b32_e64 v213, 0, -v213, vcc
	v_cndmask_b32_e64 v214, 0, -v214, s[92:93]
	v_cndmask_b32_e64 v215, 0, -v215, s[94:95]
	v_add_f32_e32 v146, v146, v213
	v_add_f32_e32 v199, v199, v146
	v_add_f32_e32 v146, v146, v214
	v_add_f32_e32 v198, v198, v146
	v_add_f32_e32 v146, v146, v215
	v_add_f32_e32 v197, v197, v146
	s_waitcnt lgkmcnt(3)
	v_exp_f32_e64 v213, -|v196|
	v_exp_f32_e64 v214, -|v195|
	v_exp_f32_e64 v215, -|v194|
	v_max_f32_e32 v216, 0, v196
	v_max_f32_e32 v217, 0, v195
	v_max_f32_e32 v218, 0, v194
	v_add_f32_e32 v213, 1.0, v213
	v_add_f32_e32 v214, 1.0, v214
	v_add_f32_e32 v215, 1.0, v215
	v_log_f32_e32 v213, v213
	v_log_f32_e32 v214, v214
	v_log_f32_e32 v215, v215
	v_cmp_lt_i32_e32 vcc, 16, v212
	v_cmp_lt_i32_e64 s[92:93], 15, v212
	v_cmp_lt_i32_e64 s[94:95], 14, v212
	v_add_f32_e32 v213, v216, v213
	v_add_f32_e32 v214, v217, v214
	v_add_f32_e32 v215, v218, v215
	v_cndmask_b32_e64 v213, 0, -v213, vcc
	v_cndmask_b32_e64 v214, 0, -v214, s[92:93]
	v_cndmask_b32_e64 v215, 0, -v215, s[94:95]
	v_add_f32_e32 v146, v146, v213
	v_add_f32_e32 v196, v196, v146
	v_add_f32_e32 v146, v146, v214
	v_add_f32_e32 v195, v195, v146
	v_add_f32_e32 v146, v146, v215
	v_add_f32_e32 v194, v194, v146
	s_waitcnt lgkmcnt(2)
	v_exp_f32_e64 v213, -|v193|
	v_exp_f32_e64 v214, -|v192|
	v_exp_f32_e64 v215, -|v191|
	v_max_f32_e32 v216, 0, v193
	v_max_f32_e32 v217, 0, v192
	v_max_f32_e32 v218, 0, v191
	v_add_f32_e32 v213, 1.0, v213
	v_add_f32_e32 v214, 1.0, v214
	v_add_f32_e32 v215, 1.0, v215
	v_log_f32_e32 v213, v213
	v_log_f32_e32 v214, v214
	v_log_f32_e32 v215, v215
	v_cmp_lt_i32_e32 vcc, 13, v212
	v_cmp_lt_i32_e64 s[92:93], 12, v212
	v_cmp_lt_i32_e64 s[94:95], 11, v212
	v_add_f32_e32 v213, v216, v213
	v_add_f32_e32 v214, v217, v214
	v_add_f32_e32 v215, v218, v215
	v_cndmask_b32_e64 v213, 0, -v213, vcc
	v_cndmask_b32_e64 v214, 0, -v214, s[92:93]
	v_cndmask_b32_e64 v215, 0, -v215, s[94:95]
	v_add_f32_e32 v146, v146, v213
	v_add_f32_e32 v193, v193, v146
	v_add_f32_e32 v146, v146, v214
	v_add_f32_e32 v192, v192, v146
	v_add_f32_e32 v146, v146, v215
	v_add_f32_e32 v191, v191, v146
	v_exp_f32_e64 v213, -|v190|
	v_exp_f32_e64 v214, -|v189|
	v_exp_f32_e64 v215, -|v188|
	v_max_f32_e32 v216, 0, v190
	v_max_f32_e32 v217, 0, v189
	v_max_f32_e32 v218, 0, v188
	v_add_f32_e32 v213, 1.0, v213
	v_add_f32_e32 v214, 1.0, v214
	v_add_f32_e32 v215, 1.0, v215
	v_log_f32_e32 v213, v213
	v_log_f32_e32 v214, v214
	v_log_f32_e32 v215, v215
	v_cmp_lt_i32_e32 vcc, 10, v212
	v_cmp_lt_i32_e64 s[92:93], 9, v212
	v_cmp_lt_i32_e64 s[94:95], 8, v212
	v_add_f32_e32 v213, v216, v213
	v_add_f32_e32 v214, v217, v214
	v_add_f32_e32 v215, v218, v215
	v_cndmask_b32_e64 v213, 0, -v213, vcc
	v_cndmask_b32_e64 v214, 0, -v214, s[92:93]
	v_cndmask_b32_e64 v215, 0, -v215, s[94:95]
	v_add_f32_e32 v146, v146, v213
	v_add_f32_e32 v190, v190, v146
	v_add_f32_e32 v146, v146, v214
	v_add_f32_e32 v189, v189, v146
	v_add_f32_e32 v146, v146, v215
	v_add_f32_e32 v188, v188, v146
	s_waitcnt lgkmcnt(1)
; __device__ __forceinline__ unsigned pack2(float a, float b) { return (unsigned)f2bf(a) | ((unsigned)f2bf(b) << 16); }
; template <int DH, int MODE>
; __device__ void attn_item(const Params& p, int layer, int b, int blk, int head, char* smem) {
;     ...
;         for (int c = 7; c >= 0; --c) {
;           float4 v = s4[c];
;           float e[4] = {v.x, v.y, v.z, v.w};
; #pragma unroll
;           for (int k = 3; k >= 0; --k) {
;             float z = e[k];
;             bool valid = (kpb + c * 4 + k) < qpos;
;             float sp = fmaxf(z, 0.f) + __builtin_amdgcn_logf(1.f + __builtin_amdgcn_exp2f(-fabsf(z)));
;             run += valid ? -sp : 0.f;
;             e[k] = z + run;
;           }
;           s4[c] = make_float4(e[0], e[1], e[2], e[3]);
;         }
;         float other = __shfl_xor(run, 1);
;         float offs = m_run + (half == 0 ? other : 0.f);
; #pragma unroll 2
;         for (int s8 = 0; s8 < 4; ++s8) {
;           float4 va = s4[2 * s8], vb = s4[2 * s8 + 1];
;           float e[8] = {va.x, va.y, va.z, va.w, vb.x, vb.y, vb.z, vb.w};
;           float pv[8];
; #pragma unroll
;           for (int k = 0; k < 8; ++k) {
;             bool valid = (kpb + s8 * 8 + k) < qpos;
;             pv[k] = valid ? __builtin_amdgcn_exp2f(e[k] + offs) : 0.f;
;           }
;           uint4 ov;
;           ov.x = pack2(pv[0], pv[1]); ov.y = pack2(pv[2], pv[3]);
;           ov.z = pack2(pv[4], pv[5]); ov.w = pack2(pv[6], pv[7]);
	v_exp_f32_e64 v213, -|v187|
	v_exp_f32_e64 v214, -|v186|
	v_exp_f32_e64 v215, -|v185|
	v_max_f32_e32 v216, 0, v187
	v_max_f32_e32 v217, 0, v186
	v_max_f32_e32 v218, 0, v185
	v_add_f32_e32 v213, 1.0, v213
	v_add_f32_e32 v214, 1.0, v214
	v_add_f32_e32 v215, 1.0, v215
	v_log_f32_e32 v213, v213
	v_log_f32_e32 v214, v214
	v_log_f32_e32 v215, v215
	v_cmp_lt_i32_e32 vcc, 7, v212
	v_cmp_lt_i32_e64 s[92:93], 6, v212
	v_cmp_lt_i32_e64 s[94:95], 5, v212
	v_add_f32_e32 v213, v216, v213
	v_add_f32_e32 v214, v217, v214
	v_add_f32_e32 v215, v218, v215
	v_cndmask_b32_e64 v213, 0, -v213, vcc
	v_cndmask_b32_e64 v214, 0, -v214, s[92:93]
	v_cndmask_b32_e64 v215, 0, -v215, s[94:95]
	v_add_f32_e32 v146, v146, v213
	v_add_f32_e32 v187, v187, v146
	v_add_f32_e32 v146, v146, v214
	v_add_f32_e32 v186, v186, v146
	v_add_f32_e32 v146, v146, v215
	v_add_f32_e32 v185, v185, v146
	s_waitcnt lgkmcnt(0)
	v_exp_f32_e64 v213, -|v184|
	v_exp_f32_e64 v214, -|v183|
	v_exp_f32_e64 v215, -|v182|
	v_max_f32_e32 v216, 0, v184
	v_max_f32_e32 v217, 0, v183
	v_max_f32_e32 v218, 0, v182
	v_add_f32_e32 v213, 1.0, v213
	v_add_f32_e32 v214, 1.0, v214
	v_add_f32_e32 v215, 1.0, v215
	v_log_f32_e32 v213, v213
	v_log_f32_e32 v214, v214
	v_log_f32_e32 v215, v215
	v_cmp_lt_i32_e32 vcc, 4, v212
	v_cmp_lt_i32_e64 s[92:93], 3, v212
	v_cmp_lt_i32_e64 s[94:95], 2, v212
	v_add_f32_e32 v213, v216, v213
	v_add_f32_e32 v214, v217, v214
	v_add_f32_e32 v215, v218, v215
	v_cndmask_b32_e64 v213, 0, -v213, vcc
	v_cndmask_b32_e64 v214, 0, -v214, s[92:93]
	v_cndmask_b32_e64 v215, 0, -v215, s[94:95]
	v_add_f32_e32 v146, v146, v213
	v_add_f32_e32 v184, v184, v146
	v_add_f32_e32 v146, v146, v214
	v_add_f32_e32 v183, v183, v146
	v_add_f32_e32 v146, v146, v215
	v_add_f32_e32 v182, v182, v146
	v_exp_f32_e64 v213, -|v181|
	v_exp_f32_e64 v214, -|v180|
	v_max_f32_e32 v216, 0, v181
	v_max_f32_e32 v217, 0, v180
	v_add_f32_e32 v213, 1.0, v213
	v_add_f32_e32 v214, 1.0, v214
	v_log_f32_e32 v213, v213
	v_log_f32_e32 v214, v214
	v_cmp_lt_i32_e32 vcc, 1, v212
	v_cmp_lt_i32_e64 s[92:93], 0, v212
	s_nop 0
	v_add_f32_e32 v213, v216, v213
	v_add_f32_e32 v214, v217, v214
	v_cndmask_b32_e64 v213, 0, -v213, vcc
	v_cndmask_b32_e64 v214, 0, -v214, s[92:93]
	v_add_f32_e32 v146, v146, v213
	v_add_f32_e32 v181, v181, v146
	v_add_f32_e32 v146, v146, v214
	v_add_f32_e32 v180, v180, v146
	ds_write_b128 v167, v[180:183]
	ds_write_b128 v167, v[184:187] offset:16
	ds_write_b128 v167, v[188:191] offset:32
	ds_write_b128 v167, v[192:195] offset:48
	ds_write_b128 v167, v[196:199] offset:64
	ds_write_b128 v167, v[200:203] offset:80
	ds_write_b128 v167, v[204:207] offset:96
	ds_write_b128 v167, v[208:211] offset:112
	ds_bpermute_b32 v147, v163, v146
	s_mov_b32 s88, 0
	v_mov_b32_e32 v175, v168
	v_mov_b32_e32 v177, v167
	s_waitcnt lgkmcnt(0)
	v_cndmask_b32_e64 v148, 0, v147, s[14:15]
	v_add_f32_e32 v176, v174, v148
	ds_read_b128 v[180:183], v177
	ds_read_b128 v[184:187], v177 offset:16
	ds_read_b128 v[188:191], v177 offset:32
	ds_read_b128 v[192:195], v177 offset:48
	ds_read_b128 v[196:199], v177 offset:64
	ds_read_b128 v[200:203], v177 offset:80
	ds_read_b128 v[204:207], v177 offset:96
	ds_read_b128 v[208:211], v177 offset:112
	v_sub_u32_e32 v212, v144, v173
	v_add_u32_e32 v212, 0xffffc040, v212
	s_waitcnt lgkmcnt(7)
	v_add_f32_e32 v180, v176, v180
	v_add_f32_e32 v181, v176, v181
	v_add_f32_e32 v182, v176, v182
	v_exp_f32_e32 v180, v180
	v_exp_f32_e32 v181, v181
	v_exp_f32_e32 v182, v182
	v_cmp_lt_i32_e32 vcc, 0, v212
	v_cmp_lt_i32_e64 s[92:93], 1, v212
	v_cmp_lt_i32_e64 s[94:95], 2, v212
	v_cndmask_b32_e32 v180, 0, v180, vcc
	v_cndmask_b32_e64 v181, 0, v181, s[92:93]
	v_cndmask_b32_e64 v182, 0, v182, s[94:95]
	s_waitcnt lgkmcnt(6)
	v_add_f32_e32 v183, v176, v183
	v_add_f32_e32 v184, v176, v184
	v_add_f32_e32 v185, v176, v185
	v_exp_f32_e32 v183, v183
	v_exp_f32_e32 v184, v184
	v_exp_f32_e32 v185, v185
	v_cmp_lt_i32_e32 vcc, 3, v212
	v_cmp_lt_i32_e64 s[92:93], 4, v212
	v_cmp_lt_i32_e64 s[94:95], 5, v212
	v_cndmask_b32_e32 v183, 0, v183, vcc
	v_cndmask_b32_e64 v184, 0, v184, s[92:93]
	v_cndmask_b32_e64 v185, 0, v185, s[94:95]
	s_waitcnt lgkmcnt(5)
; __device__ __forceinline__ unsigned pack2(float a, float b) { return (unsigned)f2bf(a) | ((unsigned)f2bf(b) << 16); }
; template <int DH, int MODE>
; __device__ void attn_item(const Params& p, int layer, int b, int blk, int head, char* smem) {
;     ...
; #pragma unroll 2
;         for (int s8 = 0; s8 < 4; ++s8) {
;           float4 va = s4[2 * s8], vb = s4[2 * s8 + 1];
;           float e[8] = {va.x, va.y, va.z, va.w, vb.x, vb.y, vb.z, vb.w};
;           float pv[8];
; #pragma unroll
;           for (int k = 0; k < 8; ++k) {
;             bool valid = (kpb + s8 * 8 + k) < qpos;
;             pv[k] = valid ? __builtin_amdgcn_exp2f(e[k] + offs) : 0.f;
;           }
;           uint4 ov;
;           ov.x = pack2(pv[0], pv[1]); ov.y = pack2(pv[2], pv[3]);
;           ov.z = pack2(pv[4], pv[5]); ov.w = pack2(pv[6], pv[7]);
;           *reinterpret_cast<uint4*>(prow + s8 * 16) = ov;
;         }
	v_add_f32_e32 v186, v176, v186
	v_add_f32_e32 v187, v176, v187
	v_add_f32_e32 v188, v176, v188
	v_exp_f32_e32 v186, v186
	v_exp_f32_e32 v187, v187
	v_exp_f32_e32 v188, v188
	v_cmp_lt_i32_e32 vcc, 6, v212
	v_cmp_lt_i32_e64 s[92:93], 7, v212
	v_cmp_lt_i32_e64 s[94:95], 8, v212
	v_cndmask_b32_e32 v186, 0, v186, vcc
	v_cndmask_b32_e64 v187, 0, v187, s[92:93]
	v_cndmask_b32_e64 v188, 0, v188, s[94:95]
	v_add_f32_e32 v189, v176, v189
	v_add_f32_e32 v190, v176, v190
	v_add_f32_e32 v191, v176, v191
	v_exp_f32_e32 v189, v189
	v_exp_f32_e32 v190, v190
	v_exp_f32_e32 v191, v191
	v_cmp_lt_i32_e32 vcc, 9, v212
	v_cmp_lt_i32_e64 s[92:93], 10, v212
	v_cmp_lt_i32_e64 s[94:95], 11, v212
	v_cndmask_b32_e32 v189, 0, v189, vcc
	v_cndmask_b32_e64 v190, 0, v190, s[92:93]
	v_cndmask_b32_e64 v191, 0, v191, s[94:95]
	s_waitcnt lgkmcnt(4)
	v_add_f32_e32 v192, v176, v192
	v_add_f32_e32 v193, v176, v193
	v_add_f32_e32 v194, v176, v194
	v_exp_f32_e32 v192, v192
	v_exp_f32_e32 v193, v193
	v_exp_f32_e32 v194, v194
	v_cmp_lt_i32_e32 vcc, 12, v212
	v_cmp_lt_i32_e64 s[92:93], 13, v212
	v_cmp_lt_i32_e64 s[94:95], 14, v212
	v_cndmask_b32_e32 v192, 0, v192, vcc
	v_cndmask_b32_e64 v193, 0, v193, s[92:93]
	v_cndmask_b32_e64 v194, 0, v194, s[94:95]
	s_waitcnt lgkmcnt(3)
	v_add_f32_e32 v195, v176, v195
	v_add_f32_e32 v196, v176, v196
	v_add_f32_e32 v197, v176, v197
	v_exp_f32_e32 v195, v195
	v_exp_f32_e32 v196, v196
	v_exp_f32_e32 v197, v197
	v_cmp_lt_i32_e32 vcc, 15, v212
	v_cmp_lt_i32_e64 s[92:93], 16, v212
	v_cmp_lt_i32_e64 s[94:95], 17, v212
	v_cndmask_b32_e32 v195, 0, v195, vcc
	v_cndmask_b32_e64 v196, 0, v196, s[92:93]
	v_cndmask_b32_e64 v197, 0, v197, s[94:95]
	s_waitcnt lgkmcnt(2)
	v_add_f32_e32 v198, v176, v198
	v_add_f32_e32 v199, v176, v199
	v_add_f32_e32 v200, v176, v200
	v_exp_f32_e32 v198, v198
	v_exp_f32_e32 v199, v199
	v_exp_f32_e32 v200, v200
	v_cmp_lt_i32_e32 vcc, 18, v212
	v_cmp_lt_i32_e64 s[92:93], 19, v212
	v_cmp_lt_i32_e64 s[94:95], 20, v212
	v_cndmask_b32_e32 v198, 0, v198, vcc
	v_cndmask_b32_e64 v199, 0, v199, s[92:93]
	v_cndmask_b32_e64 v200, 0, v200, s[94:95]
	v_add_f32_e32 v201, v176, v201
	v_add_f32_e32 v202, v176, v202
	v_add_f32_e32 v203, v176, v203
	v_exp_f32_e32 v201, v201
	v_exp_f32_e32 v202, v202
	v_exp_f32_e32 v203, v203
	v_cmp_lt_i32_e32 vcc, 21, v212
	v_cmp_lt_i32_e64 s[92:93], 22, v212
	v_cmp_lt_i32_e64 s[94:95], 23, v212
	v_cndmask_b32_e32 v201, 0, v201, vcc
	v_cndmask_b32_e64 v202, 0, v202, s[92:93]
	v_cndmask_b32_e64 v203, 0, v203, s[94:95]
	s_waitcnt lgkmcnt(1)
	v_add_f32_e32 v204, v176, v204
	v_add_f32_e32 v205, v176, v205
	v_add_f32_e32 v206, v176, v206
	v_exp_f32_e32 v204, v204
	v_exp_f32_e32 v205, v205
	v_exp_f32_e32 v206, v206
	v_cmp_lt_i32_e32 vcc, 24, v212
	v_cmp_lt_i32_e64 s[92:93], 25, v212
	v_cmp_lt_i32_e64 s[94:95], 26, v212
	v_cndmask_b32_e32 v204, 0, v204, vcc
	v_cndmask_b32_e64 v205, 0, v205, s[92:93]
	v_cndmask_b32_e64 v206, 0, v206, s[94:95]
	s_waitcnt lgkmcnt(0)
	v_add_f32_e32 v207, v176, v207
	v_add_f32_e32 v208, v176, v208
	v_add_f32_e32 v209, v176, v209
	v_exp_f32_e32 v207, v207
	v_exp_f32_e32 v208, v208
	v_exp_f32_e32 v209, v209
	v_cmp_lt_i32_e32 vcc, 27, v212
	v_cmp_lt_i32_e64 s[92:93], 28, v212
	v_cmp_lt_i32_e64 s[94:95], 29, v212
	v_cndmask_b32_e32 v207, 0, v207, vcc
	v_cndmask_b32_e64 v208, 0, v208, s[92:93]
	v_cndmask_b32_e64 v209, 0, v209, s[94:95]
	v_add_f32_e32 v210, v176, v210
	v_add_f32_e32 v211, v176, v211
	v_exp_f32_e32 v210, v210
	v_exp_f32_e32 v211, v211
	v_cmp_lt_i32_e32 vcc, 30, v212
	v_cmp_lt_i32_e64 s[92:93], 31, v212
	s_nop 0
	v_cndmask_b32_e32 v210, 0, v210, vcc
	v_cndmask_b32_e64 v211, 0, v211, s[92:93]
	v_cvt_pk_bf16_f32 v148, v180, v181
	v_cvt_pk_bf16_f32 v149, v182, v183
	v_cvt_pk_bf16_f32 v150, v184, v185
	v_cvt_pk_bf16_f32 v151, v186, v187
	ds_write_b128 v175, v[148:151]
	s_nop 0
	v_cvt_pk_bf16_f32 v148, v188, v189
	v_cvt_pk_bf16_f32 v149, v190, v191
	v_cvt_pk_bf16_f32 v150, v192, v193
	v_cvt_pk_bf16_f32 v151, v194, v195
	ds_write_b128 v175, v[148:151] offset:16
	s_nop 0
	v_cvt_pk_bf16_f32 v148, v196, v197
	v_cvt_pk_bf16_f32 v149, v198, v199
	v_cvt_pk_bf16_f32 v150, v200, v201
	v_cvt_pk_bf16_f32 v151, v202, v203
	ds_write_b128 v175, v[148:151] offset:32
	s_nop 0
	v_cvt_pk_bf16_f32 v148, v204, v205
	v_cvt_pk_bf16_f32 v149, v206, v207
	v_cvt_pk_bf16_f32 v150, v208, v209
	v_cvt_pk_bf16_f32 v151, v210, v211
	ds_write_b128 v175, v[148:151] offset:48
	s_branch .LBB0_534

; template <int DH, int MODE>
; __device__ void attn_item(const Params& p, int layer, int b, int blk, int head, char* smem) {
;     ...
;         const int kpb = ktok + half * 32;
;         float run = 0.f;
; #pragma unroll 2
;         for (int c = 7; c >= 0; --c) {
;           float4 v = s4[c];
;           float e[4] = {v.x, v.y, v.z, v.w};
; #pragma unroll
;           for (int k = 3; k >= 0; --k) {
;             float z = e[k];
;             bool valid = (kpb + c * 4 + k) < qpos;
;             float sp = fmaxf(z, 0.f) + __builtin_amdgcn_logf(1.f + __builtin_amdgcn_exp2f(-fabsf(z)));
;             run += valid ? -sp : 0.f;
;             e[k] = z + run;
;           }
;           s4[c] = make_float4(e[0], e[1], e[2], e[3]);
;         }
.LBB0_845:
	s_or_b64 exec, exec, s[50:51]
	s_add_i32 s36, s87, 1
	s_min_i32 s50, s36, s85
	s_sub_i32 s50, s85, s50
	s_lshl_b32 s50, s50, 6
	s_ashr_i32 s51, s50, 31
	s_add_u32 s50, s50, s84
	s_addc_u32 s51, s51, 0
	s_waitcnt lgkmcnt(0)
	s_barrier
	ds_write_b16 v171, v96
	ds_write_b16_d16_hi v171, v96 offset:64
	ds_write_b16 v171, v97 offset:128
	ds_write_b16_d16_hi v171, v97 offset:192
	ds_write_b16 v171, v98 offset:256
	ds_write_b16_d16_hi v171, v98 offset:320
	ds_write_b16 v171, v99 offset:384
	ds_write_b16_d16_hi v171, v99 offset:448
	ds_write_b16 v171, v100 offset:2048
	ds_write_b16_d16_hi v171, v100 offset:2112
	ds_write_b16 v171, v101 offset:2176
	ds_write_b16_d16_hi v171, v101 offset:2240
	ds_write_b16 v171, v102 offset:2304
	ds_write_b16_d16_hi v171, v102 offset:2368
	ds_write_b16 v171, v103 offset:2432
	ds_write_b16_d16_hi v171, v103 offset:2496
	s_waitcnt vmcnt(1)
	ds_write_b16 v171, v108 offset:4096
	ds_write_b16_d16_hi v171, v108 offset:4160
	ds_write_b16 v171, v109 offset:4224
	ds_write_b16_d16_hi v171, v109 offset:4288
	ds_write_b16 v171, v110 offset:4352
	ds_write_b16_d16_hi v171, v110 offset:4416
	ds_write_b16 v171, v111 offset:4480
	ds_write_b16_d16_hi v171, v111 offset:4544
	s_waitcnt vmcnt(0)
	ds_write_b16 v171, v104 offset:6144
	ds_write_b16_d16_hi v171, v104 offset:6208
	ds_write_b16 v171, v105 offset:6272
	ds_write_b16_d16_hi v171, v105 offset:6336
	ds_write_b16 v171, v106 offset:6400
	ds_write_b16_d16_hi v171, v106 offset:6464
	ds_write_b16 v171, v107 offset:6528
	ds_write_b16_d16_hi v171, v107 offset:6592
	v_lshl_add_u64 v[96:97], s[50:51], 0, v[134:135]
	v_mad_u64_u32 v[104:105], s[52:53], v96, s45, v[140:141]
	v_or_b32_e32 v96, s50, v132
	v_mad_i32_i24 v105, v97, s45, v105
	v_mad_u64_u32 v[106:107], s[52:53], v96, s45, v[142:143]
	v_add_co_u32_e32 v96, vcc, s71, v104
	v_mad_i32_i24 v107, s51, v160, v107
	s_nop 0
	v_addc_co_u32_e32 v97, vcc, 0, v105, vcc
	v_add_co_u32_e32 v98, vcc, 0x4c000, v104
	s_nop 1
	v_addc_co_u32_e32 v99, vcc, 0, v105, vcc
	v_add_co_u32_e32 v100, vcc, 0x72000, v104
	global_load_dwordx4 v[120:123], v[96:97], off
	global_load_dwordx4 v[116:119], v[98:99], off
	v_addc_co_u32_e32 v101, vcc, 0, v105, vcc
	global_load_dwordx4 v[96:99], v[106:107], off
	global_load_dwordx4 v[124:127], v[100:101], off
	s_nop 0
	global_load_dwordx4 v[100:103], v[106:107], off offset:64
	global_load_dwordx4 v[108:111], v[106:107], off offset:128
	global_load_dwordx4 v[112:115], v[104:105], off
	s_nop 0
	global_load_dwordx4 v[104:107], v[106:107], off offset:192
	s_and_saveexec_b64 s[50:51], s[16:17]
	s_cbranch_execz .LBB0_856
	v_mov_b32_e32 v146, 0
	s_mov_b32 s52, 0
	v_mov_b32_e32 v148, v166
	ds_read_b128 v[208:211], v167 offset:112
	ds_read_b128 v[204:207], v167 offset:96
	ds_read_b128 v[200:203], v167 offset:80
	ds_read_b128 v[196:199], v167 offset:64
	ds_read_b128 v[192:195], v167 offset:48
	ds_read_b128 v[188:191], v167 offset:32
	ds_read_b128 v[184:187], v167 offset:16
	ds_read_b128 v[180:183], v167
	v_sub_u32_e32 v212, v144, v173
	v_add_u32_e32 v212, 0xffffc040, v212
	s_waitcnt lgkmcnt(7)
	v_exp_f32_e64 v213, -|v211|
	v_exp_f32_e64 v214, -|v210|
	v_exp_f32_e64 v215, -|v209|
	v_max_f32_e32 v216, 0, v211
	v_max_f32_e32 v217, 0, v210
	v_max_f32_e32 v218, 0, v209
	v_add_f32_e32 v213, 1.0, v213
	v_add_f32_e32 v214, 1.0, v214
	v_add_f32_e32 v215, 1.0, v215
	v_log_f32_e32 v213, v213
	v_log_f32_e32 v214, v214
	v_log_f32_e32 v215, v215
	v_cmp_lt_i32_e32 vcc, 31, v212
	v_cmp_lt_i32_e64 s[92:93], 30, v212
	v_cmp_lt_i32_e64 s[94:95], 29, v212
	v_add_f32_e32 v213, v216, v213
	v_add_f32_e32 v214, v217, v214
	v_add_f32_e32 v215, v218, v215
	v_cndmask_b32_e64 v213, 0, -v213, vcc
	v_cndmask_b32_e64 v214, 0, -v214, s[92:93]
	v_cndmask_b32_e64 v215, 0, -v215, s[94:95]
	v_add_f32_e32 v146, v146, v213
	v_add_f32_e32 v211, v211, v146
	v_add_f32_e32 v146, v146, v214
	v_add_f32_e32 v210, v210, v146
	v_add_f32_e32 v146, v146, v215
	v_add_f32_e32 v209, v209, v146
	s_waitcnt lgkmcnt(6)
	v_exp_f32_e64 v213, -|v208|
	v_exp_f32_e64 v214, -|v207|
	v_exp_f32_e64 v215, -|v206|
	v_max_f32_e32 v216, 0, v208
	v_max_f32_e32 v217, 0, v207
	v_max_f32_e32 v218, 0, v206
	v_add_f32_e32 v213, 1.0, v213
	v_add_f32_e32 v214, 1.0, v214
	v_add_f32_e32 v215, 1.0, v215
	v_log_f32_e32 v213, v213
	v_log_f32_e32 v214, v214
	v_log_f32_e32 v215, v215
	v_cmp_lt_i32_e32 vcc, 28, v212
	v_cmp_lt_i32_e64 s[92:93], 27, v212
	v_cmp_lt_i32_e64 s[94:95], 26, v212
	v_add_f32_e32 v213, v216, v213
	v_add_f32_e32 v214, v217, v214
	v_add_f32_e32 v215, v218, v215
	v_cndmask_b32_e64 v213, 0, -v213, vcc
	v_cndmask_b32_e64 v214, 0, -v214, s[92:93]
	v_cndmask_b32_e64 v215, 0, -v215, s[94:95]
	v_add_f32_e32 v146, v146, v213
	v_add_f32_e32 v208, v208, v146
	v_add_f32_e32 v146, v146, v214
	v_add_f32_e32 v207, v207, v146
	v_add_f32_e32 v146, v146, v215
	v_add_f32_e32 v206, v206, v146
	s_waitcnt lgkmcnt(5)
; template <int DH, int MODE>
; __device__ void attn_item(const Params& p, int layer, int b, int blk, int head, char* smem) {
;     ...
; #pragma unroll 2
;         for (int c = 7; c >= 0; --c) {
;           float4 v = s4[c];
;           float e[4] = {v.x, v.y, v.z, v.w};
; #pragma unroll
;           for (int k = 3; k >= 0; --k) {
;             float z = e[k];
;             bool valid = (kpb + c * 4 + k) < qpos;
;             float sp = fmaxf(z, 0.f) + __builtin_amdgcn_logf(1.f + __builtin_amdgcn_exp2f(-fabsf(z)));
;             run += valid ? -sp : 0.f;
;             e[k] = z + run;
;           }
;           s4[c] = make_float4(e[0], e[1], e[2], e[3]);
;         }
	v_exp_f32_e64 v213, -|v205|
	v_exp_f32_e64 v214, -|v204|
	v_exp_f32_e64 v215, -|v203|
	v_max_f32_e32 v216, 0, v205
	v_max_f32_e32 v217, 0, v204
	v_max_f32_e32 v218, 0, v203
	v_add_f32_e32 v213, 1.0, v213
	v_add_f32_e32 v214, 1.0, v214
	v_add_f32_e32 v215, 1.0, v215
	v_log_f32_e32 v213, v213
	v_log_f32_e32 v214, v214
	v_log_f32_e32 v215, v215
	v_cmp_lt_i32_e32 vcc, 25, v212
	v_cmp_lt_i32_e64 s[92:93], 24, v212
	v_cmp_lt_i32_e64 s[94:95], 23, v212
	v_add_f32_e32 v213, v216, v213
	v_add_f32_e32 v214, v217, v214
	v_add_f32_e32 v215, v218, v215
	v_cndmask_b32_e64 v213, 0, -v213, vcc
	v_cndmask_b32_e64 v214, 0, -v214, s[92:93]
	v_cndmask_b32_e64 v215, 0, -v215, s[94:95]
	v_add_f32_e32 v146, v146, v213
	v_add_f32_e32 v205, v205, v146
	v_add_f32_e32 v146, v146, v214
	v_add_f32_e32 v204, v204, v146
	v_add_f32_e32 v146, v146, v215
	v_add_f32_e32 v203, v203, v146
	v_exp_f32_e64 v213, -|v202|
	v_exp_f32_e64 v214, -|v201|
	v_exp_f32_e64 v215, -|v200|
	v_max_f32_e32 v216, 0, v202
	v_max_f32_e32 v217, 0, v201
	v_max_f32_e32 v218, 0, v200
	v_add_f32_e32 v213, 1.0, v213
	v_add_f32_e32 v214, 1.0, v214
	v_add_f32_e32 v215, 1.0, v215
	v_log_f32_e32 v213, v213
	v_log_f32_e32 v214, v214
	v_log_f32_e32 v215, v215
	v_cmp_lt_i32_e32 vcc, 22, v212
	v_cmp_lt_i32_e64 s[92:93], 21, v212
	v_cmp_lt_i32_e64 s[94:95], 20, v212
	v_add_f32_e32 v213, v216, v213
	v_add_f32_e32 v214, v217, v214
	v_add_f32_e32 v215, v218, v215
	v_cndmask_b32_e64 v213, 0, -v213, vcc
	v_cndmask_b32_e64 v214, 0, -v214, s[92:93]
	v_cndmask_b32_e64 v215, 0, -v215, s[94:95]
	v_add_f32_e32 v146, v146, v213
	v_add_f32_e32 v202, v202, v146
	v_add_f32_e32 v146, v146, v214
	v_add_f32_e32 v201, v201, v146
	v_add_f32_e32 v146, v146, v215
	v_add_f32_e32 v200, v200, v146
	s_waitcnt lgkmcnt(4)
	v_exp_f32_e64 v213, -|v199|
	v_exp_f32_e64 v214, -|v198|
	v_exp_f32_e64 v215, -|v197|
	v_max_f32_e32 v216, 0, v199
	v_max_f32_e32 v217, 0, v198
	v_max_f32_e32 v218, 0, v197
	v_add_f32_e32 v213, 1.0, v213
	v_add_f32_e32 v214, 1.0, v214
	v_add_f32_e32 v215, 1.0, v215
	v_log_f32_e32 v213, v213
	v_log_f32_e32 v214, v214
	v_log_f32_e32 v215, v215
	v_cmp_lt_i32_e32 vcc, 19, v212
	v_cmp_lt_i32_e64 s[92:93], 18, v212
	v_cmp_lt_i32_e64 s[94:95], 17, v212
	v_add_f32_e32 v213, v216, v213
	v_add_f32_e32 v214, v217, v214
	v_add_f32_e32 v215, v218, v215
	v_cndmask_b32_e64 v213, 0, -v213, vcc
	v_cndmask_b32_e64 v214, 0, -v214, s[92:93]
	v_cndmask_b32_e64 v215, 0, -v215, s[94:95]
	v_add_f32_e32 v146, v146, v213
	v_add_f32_e32 v199, v199, v146
	v_add_f32_e32 v146, v146, v214
	v_add_f32_e32 v198, v198, v146
	v_add_f32_e32 v146, v146, v215
	v_add_f32_e32 v197, v197, v146
	s_waitcnt lgkmcnt(3)
	v_exp_f32_e64 v213, -|v196|
	v_exp_f32_e64 v214, -|v195|
	v_exp_f32_e64 v215, -|v194|
	v_max_f32_e32 v216, 0, v196
	v_max_f32_e32 v217, 0, v195
	v_max_f32_e32 v218, 0, v194
	v_add_f32_e32 v213, 1.0, v213
	v_add_f32_e32 v214, 1.0, v214
	v_add_f32_e32 v215, 1.0, v215
	v_log_f32_e32 v213, v213
	v_log_f32_e32 v214, v214
	v_log_f32_e32 v215, v215
	v_cmp_lt_i32_e32 vcc, 16, v212
	v_cmp_lt_i32_e64 s[92:93], 15, v212
	v_cmp_lt_i32_e64 s[94:95], 14, v212
	v_add_f32_e32 v213, v216, v213
	v_add_f32_e32 v214, v217, v214
	v_add_f32_e32 v215, v218, v215
	v_cndmask_b32_e64 v213, 0, -v213, vcc
	v_cndmask_b32_e64 v214, 0, -v214, s[92:93]
	v_cndmask_b32_e64 v215, 0, -v215, s[94:95]
	v_add_f32_e32 v146, v146, v213
	v_add_f32_e32 v196, v196, v146
	v_add_f32_e32 v146, v146, v214
	v_add_f32_e32 v195, v195, v146
	v_add_f32_e32 v146, v146, v215
	v_add_f32_e32 v194, v194, v146
	s_waitcnt lgkmcnt(2)
	v_exp_f32_e64 v213, -|v193|
	v_exp_f32_e64 v214, -|v192|
	v_exp_f32_e64 v215, -|v191|
	v_max_f32_e32 v216, 0, v193
	v_max_f32_e32 v217, 0, v192
	v_max_f32_e32 v218, 0, v191
	v_add_f32_e32 v213, 1.0, v213
	v_add_f32_e32 v214, 1.0, v214
	v_add_f32_e32 v215, 1.0, v215
	v_log_f32_e32 v213, v213
	v_log_f32_e32 v214, v214
	v_log_f32_e32 v215, v215
	v_cmp_lt_i32_e32 vcc, 13, v212
	v_cmp_lt_i32_e64 s[92:93], 12, v212
	v_cmp_lt_i32_e64 s[94:95], 11, v212
	v_add_f32_e32 v213, v216, v213
	v_add_f32_e32 v214, v217, v214
	v_add_f32_e32 v215, v218, v215
	v_cndmask_b32_e64 v213, 0, -v213, vcc
	v_cndmask_b32_e64 v214, 0, -v214, s[92:93]
	v_cndmask_b32_e64 v215, 0, -v215, s[94:95]
	v_add_f32_e32 v146, v146, v213
	v_add_f32_e32 v193, v193, v146
	v_add_f32_e32 v146, v146, v214
	v_add_f32_e32 v192, v192, v146
	v_add_f32_e32 v146, v146, v215
	v_add_f32_e32 v191, v191, v146
	v_exp_f32_e64 v213, -|v190|
	v_exp_f32_e64 v214, -|v189|
	v_exp_f32_e64 v215, -|v188|
	v_max_f32_e32 v216, 0, v190
	v_max_f32_e32 v217, 0, v189
	v_max_f32_e32 v218, 0, v188
	v_add_f32_e32 v213, 1.0, v213
	v_add_f32_e32 v214, 1.0, v214
	v_add_f32_e32 v215, 1.0, v215
	v_log_f32_e32 v213, v213
	v_log_f32_e32 v214, v214
	v_log_f32_e32 v215, v215
	v_cmp_lt_i32_e32 vcc, 10, v212
	v_cmp_lt_i32_e64 s[92:93], 9, v212
	v_cmp_lt_i32_e64 s[94:95], 8, v212
	v_add_f32_e32 v213, v216, v213
	v_add_f32_e32 v214, v217, v214
	v_add_f32_e32 v215, v218, v215
	v_cndmask_b32_e64 v213, 0, -v213, vcc
	v_cndmask_b32_e64 v214, 0, -v214, s[92:93]
	v_cndmask_b32_e64 v215, 0, -v215, s[94:95]
	v_add_f32_e32 v146, v146, v213
	v_add_f32_e32 v190, v190, v146
	v_add_f32_e32 v146, v146, v214
	v_add_f32_e32 v189, v189, v146
	v_add_f32_e32 v146, v146, v215
	v_add_f32_e32 v188, v188, v146
	s_waitcnt lgkmcnt(1)
; __device__ __forceinline__ unsigned pack2(float a, float b) { return (unsigned)f2bf(a) | ((unsigned)f2bf(b) << 16); }
; template <int DH, int MODE>
; __device__ void attn_item(const Params& p, int layer, int b, int blk, int head, char* smem) {
;     ...
; #pragma unroll 2
;         for (int c = 7; c >= 0; --c) {
;           float4 v = s4[c];
;           float e[4] = {v.x, v.y, v.z, v.w};
; #pragma unroll
;           for (int k = 3; k >= 0; --k) {
;             float z = e[k];
;             bool valid = (kpb + c * 4 + k) < qpos;
;             float sp = fmaxf(z, 0.f) + __builtin_amdgcn_logf(1.f + __builtin_amdgcn_exp2f(-fabsf(z)));
;             run += valid ? -sp : 0.f;
;             e[k] = z + run;
;           }
;           s4[c] = make_float4(e[0], e[1], e[2], e[3]);
;         }
;         float other = __shfl_xor(run, 1);
;         float offs = m_run + (half == 0 ? other : 0.f);
; #pragma unroll 2
;         for (int s8 = 0; s8 < 4; ++s8) {
;           float4 va = s4[2 * s8], vb = s4[2 * s8 + 1];
;           float e[8] = {va.x, va.y, va.z, va.w, vb.x, vb.y, vb.z, vb.w};
;           float pv[8];
; #pragma unroll
;           for (int k = 0; k < 8; ++k) {
;             bool valid = (kpb + s8 * 8 + k) < qpos;
;             pv[k] = valid ? __builtin_amdgcn_exp2f(e[k] + offs) : 0.f;
;           }
;           uint4 ov;
;           ov.x = pack2(pv[0], pv[1]); ov.y = pack2(pv[2], pv[3]);
;           ov.z = pack2(pv[4], pv[5]); ov.w = pack2(pv[6], pv[7]);
;           *reinterpret_cast<uint4*>(prow + s8 * 16) = ov;
;         }
	v_exp_f32_e64 v213, -|v187|
	v_exp_f32_e64 v214, -|v186|
	v_exp_f32_e64 v215, -|v185|
	v_max_f32_e32 v216, 0, v187
	v_max_f32_e32 v217, 0, v186
	v_max_f32_e32 v218, 0, v185
	v_add_f32_e32 v213, 1.0, v213
	v_add_f32_e32 v214, 1.0, v214
	v_add_f32_e32 v215, 1.0, v215
	v_log_f32_e32 v213, v213
	v_log_f32_e32 v214, v214
	v_log_f32_e32 v215, v215
	v_cmp_lt_i32_e32 vcc, 7, v212
	v_cmp_lt_i32_e64 s[92:93], 6, v212
	v_cmp_lt_i32_e64 s[94:95], 5, v212
	v_add_f32_e32 v213, v216, v213
	v_add_f32_e32 v214, v217, v214
	v_add_f32_e32 v215, v218, v215
	v_cndmask_b32_e64 v213, 0, -v213, vcc
	v_cndmask_b32_e64 v214, 0, -v214, s[92:93]
	v_cndmask_b32_e64 v215, 0, -v215, s[94:95]
	v_add_f32_e32 v146, v146, v213
	v_add_f32_e32 v187, v187, v146
	v_add_f32_e32 v146, v146, v214
	v_add_f32_e32 v186, v186, v146
	v_add_f32_e32 v146, v146, v215
	v_add_f32_e32 v185, v185, v146
	s_waitcnt lgkmcnt(0)
	v_exp_f32_e64 v213, -|v184|
	v_exp_f32_e64 v214, -|v183|
	v_exp_f32_e64 v215, -|v182|
	v_max_f32_e32 v216, 0, v184
	v_max_f32_e32 v217, 0, v183
	v_max_f32_e32 v218, 0, v182
	v_add_f32_e32 v213, 1.0, v213
	v_add_f32_e32 v214, 1.0, v214
	v_add_f32_e32 v215, 1.0, v215
	v_log_f32_e32 v213, v213
	v_log_f32_e32 v214, v214
	v_log_f32_e32 v215, v215
	v_cmp_lt_i32_e32 vcc, 4, v212
	v_cmp_lt_i32_e64 s[92:93], 3, v212
	v_cmp_lt_i32_e64 s[94:95], 2, v212
	v_add_f32_e32 v213, v216, v213
	v_add_f32_e32 v214, v217, v214
	v_add_f32_e32 v215, v218, v215
	v_cndmask_b32_e64 v213, 0, -v213, vcc
	v_cndmask_b32_e64 v214, 0, -v214, s[92:93]
	v_cndmask_b32_e64 v215, 0, -v215, s[94:95]
	v_add_f32_e32 v146, v146, v213
	v_add_f32_e32 v184, v184, v146
	v_add_f32_e32 v146, v146, v214
	v_add_f32_e32 v183, v183, v146
	v_add_f32_e32 v146, v146, v215
	v_add_f32_e32 v182, v182, v146
	v_exp_f32_e64 v213, -|v181|
	v_exp_f32_e64 v214, -|v180|
	v_max_f32_e32 v216, 0, v181
	v_max_f32_e32 v217, 0, v180
	v_add_f32_e32 v213, 1.0, v213
	v_add_f32_e32 v214, 1.0, v214
	v_log_f32_e32 v213, v213
	v_log_f32_e32 v214, v214
	v_cmp_lt_i32_e32 vcc, 1, v212
	v_cmp_lt_i32_e64 s[92:93], 0, v212
	s_nop 0
	v_add_f32_e32 v213, v216, v213
	v_add_f32_e32 v214, v217, v214
	v_cndmask_b32_e64 v213, 0, -v213, vcc
	v_cndmask_b32_e64 v214, 0, -v214, s[92:93]
	v_add_f32_e32 v146, v146, v213
	v_add_f32_e32 v181, v181, v146
	v_add_f32_e32 v146, v146, v214
	v_add_f32_e32 v180, v180, v146
	ds_write_b128 v167, v[180:183]
	ds_write_b128 v167, v[184:187] offset:16
	ds_write_b128 v167, v[188:191] offset:32
	ds_write_b128 v167, v[192:195] offset:48
	ds_write_b128 v167, v[196:199] offset:64
	ds_write_b128 v167, v[200:203] offset:80
	ds_write_b128 v167, v[204:207] offset:96
	ds_write_b128 v167, v[208:211] offset:112
	ds_bpermute_b32 v147, v163, v146
	s_mov_b32 s88, 0
	v_mov_b32_e32 v175, v168
	v_mov_b32_e32 v177, v167
	s_waitcnt lgkmcnt(0)
	v_cndmask_b32_e64 v148, 0, v147, s[14:15]
	v_add_f32_e32 v176, v174, v148
	ds_read_b128 v[180:183], v177
	ds_read_b128 v[184:187], v177 offset:16
	ds_read_b128 v[188:191], v177 offset:32
	ds_read_b128 v[192:195], v177 offset:48
	ds_read_b128 v[196:199], v177 offset:64
	ds_read_b128 v[200:203], v177 offset:80
	ds_read_b128 v[204:207], v177 offset:96
	ds_read_b128 v[208:211], v177 offset:112
	v_sub_u32_e32 v212, v144, v173
	v_add_u32_e32 v212, 0xffffc040, v212
	s_waitcnt lgkmcnt(7)
	v_add_f32_e32 v180, v176, v180
	v_add_f32_e32 v181, v176, v181
	v_add_f32_e32 v182, v176, v182
	v_exp_f32_e32 v180, v180
	v_exp_f32_e32 v181, v181
	v_exp_f32_e32 v182, v182
	v_cmp_lt_i32_e32 vcc, 0, v212
	v_cmp_lt_i32_e64 s[92:93], 1, v212
	v_cmp_lt_i32_e64 s[94:95], 2, v212
	v_cndmask_b32_e32 v180, 0, v180, vcc
	v_cndmask_b32_e64 v181, 0, v181, s[92:93]
	v_cndmask_b32_e64 v182, 0, v182, s[94:95]
	s_waitcnt lgkmcnt(6)
	v_add_f32_e32 v183, v176, v183
	v_add_f32_e32 v184, v176, v184
	v_add_f32_e32 v185, v176, v185
	v_exp_f32_e32 v183, v183
	v_exp_f32_e32 v184, v184
	v_exp_f32_e32 v185, v185
	v_cmp_lt_i32_e32 vcc, 3, v212
	v_cmp_lt_i32_e64 s[92:93], 4, v212
	v_cmp_lt_i32_e64 s[94:95], 5, v212
	v_cndmask_b32_e32 v183, 0, v183, vcc
	v_cndmask_b32_e64 v184, 0, v184, s[92:93]
	v_cndmask_b32_e64 v185, 0, v185, s[94:95]
	s_waitcnt lgkmcnt(5)
; __device__ __forceinline__ unsigned pack2(float a, float b) { return (unsigned)f2bf(a) | ((unsigned)f2bf(b) << 16); }
; template <int DH, int MODE>
; __device__ void attn_item(const Params& p, int layer, int b, int blk, int head, char* smem) {
;     ...
; #pragma unroll 2
;         for (int s8 = 0; s8 < 4; ++s8) {
;           float4 va = s4[2 * s8], vb = s4[2 * s8 + 1];
;           float e[8] = {va.x, va.y, va.z, va.w, vb.x, vb.y, vb.z, vb.w};
;           float pv[8];
; #pragma unroll
;           for (int k = 0; k < 8; ++k) {
;             bool valid = (kpb + s8 * 8 + k) < qpos;
;             pv[k] = valid ? __builtin_amdgcn_exp2f(e[k] + offs) : 0.f;
;           }
;           uint4 ov;
;           ov.x = pack2(pv[0], pv[1]); ov.y = pack2(pv[2], pv[3]);
;           ov.z = pack2(pv[4], pv[5]); ov.w = pack2(pv[6], pv[7]);
;           *reinterpret_cast<uint4*>(prow + s8 * 16) = ov;
;         }
	v_add_f32_e32 v186, v176, v186
	v_add_f32_e32 v187, v176, v187
	v_add_f32_e32 v188, v176, v188
	v_exp_f32_e32 v186, v186
	v_exp_f32_e32 v187, v187
	v_exp_f32_e32 v188, v188
	v_cmp_lt_i32_e32 vcc, 6, v212
	v_cmp_lt_i32_e64 s[92:93], 7, v212
	v_cmp_lt_i32_e64 s[94:95], 8, v212
	v_cndmask_b32_e32 v186, 0, v186, vcc
	v_cndmask_b32_e64 v187, 0, v187, s[92:93]
	v_cndmask_b32_e64 v188, 0, v188, s[94:95]
	v_add_f32_e32 v189, v176, v189
	v_add_f32_e32 v190, v176, v190
	v_add_f32_e32 v191, v176, v191
	v_exp_f32_e32 v189, v189
	v_exp_f32_e32 v190, v190
	v_exp_f32_e32 v191, v191
	v_cmp_lt_i32_e32 vcc, 9, v212
	v_cmp_lt_i32_e64 s[92:93], 10, v212
	v_cmp_lt_i32_e64 s[94:95], 11, v212
	v_cndmask_b32_e32 v189, 0, v189, vcc
	v_cndmask_b32_e64 v190, 0, v190, s[92:93]
	v_cndmask_b32_e64 v191, 0, v191, s[94:95]
	s_waitcnt lgkmcnt(4)
	v_add_f32_e32 v192, v176, v192
	v_add_f32_e32 v193, v176, v193
	v_add_f32_e32 v194, v176, v194
	v_exp_f32_e32 v192, v192
	v_exp_f32_e32 v193, v193
	v_exp_f32_e32 v194, v194
	v_cmp_lt_i32_e32 vcc, 12, v212
	v_cmp_lt_i32_e64 s[92:93], 13, v212
	v_cmp_lt_i32_e64 s[94:95], 14, v212
	v_cndmask_b32_e32 v192, 0, v192, vcc
	v_cndmask_b32_e64 v193, 0, v193, s[92:93]
	v_cndmask_b32_e64 v194, 0, v194, s[94:95]
	s_waitcnt lgkmcnt(3)
	v_add_f32_e32 v195, v176, v195
	v_add_f32_e32 v196, v176, v196
	v_add_f32_e32 v197, v176, v197
	v_exp_f32_e32 v195, v195
	v_exp_f32_e32 v196, v196
	v_exp_f32_e32 v197, v197
	v_cmp_lt_i32_e32 vcc, 15, v212
	v_cmp_lt_i32_e64 s[92:93], 16, v212
	v_cmp_lt_i32_e64 s[94:95], 17, v212
	v_cndmask_b32_e32 v195, 0, v195, vcc
	v_cndmask_b32_e64 v196, 0, v196, s[92:93]
	v_cndmask_b32_e64 v197, 0, v197, s[94:95]
	s_waitcnt lgkmcnt(2)
	v_add_f32_e32 v198, v176, v198
	v_add_f32_e32 v199, v176, v199
	v_add_f32_e32 v200, v176, v200
	v_exp_f32_e32 v198, v198
	v_exp_f32_e32 v199, v199
	v_exp_f32_e32 v200, v200
	v_cmp_lt_i32_e32 vcc, 18, v212
	v_cmp_lt_i32_e64 s[92:93], 19, v212
	v_cmp_lt_i32_e64 s[94:95], 20, v212
	v_cndmask_b32_e32 v198, 0, v198, vcc
	v_cndmask_b32_e64 v199, 0, v199, s[92:93]
	v_cndmask_b32_e64 v200, 0, v200, s[94:95]
	v_add_f32_e32 v201, v176, v201
	v_add_f32_e32 v202, v176, v202
	v_add_f32_e32 v203, v176, v203
	v_exp_f32_e32 v201, v201
	v_exp_f32_e32 v202, v202
	v_exp_f32_e32 v203, v203
	v_cmp_lt_i32_e32 vcc, 21, v212
	v_cmp_lt_i32_e64 s[92:93], 22, v212
	v_cmp_lt_i32_e64 s[94:95], 23, v212
	v_cndmask_b32_e32 v201, 0, v201, vcc
	v_cndmask_b32_e64 v202, 0, v202, s[92:93]
	v_cndmask_b32_e64 v203, 0, v203, s[94:95]
	s_waitcnt lgkmcnt(1)
	v_add_f32_e32 v204, v176, v204
	v_add_f32_e32 v205, v176, v205
	v_add_f32_e32 v206, v176, v206
	v_exp_f32_e32 v204, v204
	v_exp_f32_e32 v205, v205
	v_exp_f32_e32 v206, v206
	v_cmp_lt_i32_e32 vcc, 24, v212
	v_cmp_lt_i32_e64 s[92:93], 25, v212
	v_cmp_lt_i32_e64 s[94:95], 26, v212
	v_cndmask_b32_e32 v204, 0, v204, vcc
	v_cndmask_b32_e64 v205, 0, v205, s[92:93]
	v_cndmask_b32_e64 v206, 0, v206, s[94:95]
	s_waitcnt lgkmcnt(0)
	v_add_f32_e32 v207, v176, v207
	v_add_f32_e32 v208, v176, v208
	v_add_f32_e32 v209, v176, v209
	v_exp_f32_e32 v207, v207
	v_exp_f32_e32 v208, v208
	v_exp_f32_e32 v209, v209
	v_cmp_lt_i32_e32 vcc, 27, v212
	v_cmp_lt_i32_e64 s[92:93], 28, v212
	v_cmp_lt_i32_e64 s[94:95], 29, v212
	v_cndmask_b32_e32 v207, 0, v207, vcc
	v_cndmask_b32_e64 v208, 0, v208, s[92:93]
	v_cndmask_b32_e64 v209, 0, v209, s[94:95]
	v_add_f32_e32 v210, v176, v210
	v_add_f32_e32 v211, v176, v211
	v_exp_f32_e32 v210, v210
	v_exp_f32_e32 v211, v211
	v_cmp_lt_i32_e32 vcc, 30, v212
	v_cmp_lt_i32_e64 s[92:93], 31, v212
	s_nop 0
	v_cndmask_b32_e32 v210, 0, v210, vcc
	v_cndmask_b32_e64 v211, 0, v211, s[92:93]
	v_cvt_pk_bf16_f32 v148, v180, v181
	v_cvt_pk_bf16_f32 v149, v182, v183
	v_cvt_pk_bf16_f32 v150, v184, v185
	v_cvt_pk_bf16_f32 v151, v186, v187
	ds_write_b128 v175, v[148:151]
	s_nop 0
	v_cvt_pk_bf16_f32 v148, v188, v189
	v_cvt_pk_bf16_f32 v149, v190, v191
	v_cvt_pk_bf16_f32 v150, v192, v193
	v_cvt_pk_bf16_f32 v151, v194, v195
	ds_write_b128 v175, v[148:151] offset:16
	s_nop 0
	v_cvt_pk_bf16_f32 v148, v196, v197
	v_cvt_pk_bf16_f32 v149, v198, v199
	v_cvt_pk_bf16_f32 v150, v200, v201
	v_cvt_pk_bf16_f32 v151, v202, v203
	ds_write_b128 v175, v[148:151] offset:32
	s_nop 0
	v_cvt_pk_bf16_f32 v148, v204, v205
	v_cvt_pk_bf16_f32 v149, v206, v207
	v_cvt_pk_bf16_f32 v150, v208, v209
	v_cvt_pk_bf16_f32 v151, v210, v211
	ds_write_b128 v175, v[148:151] offset:48
	s_branch .LBB0_855

; template <int DH, int MODE>
; __device__ void attn_item(const Params& p, int layer, int b, int blk, int head, char* smem) {
;     ...
;         const int kpb = ktok + half * 32;
;         float run = 0.f;
; #pragma unroll 2
;         for (int c = 7; c >= 0; --c) {
;           float4 v = s4[c];
;           float e[4] = {v.x, v.y, v.z, v.w};
; #pragma unroll
;           for (int k = 3; k >= 0; --k) {
;             float z = e[k];
;             bool valid = (kpb + c * 4 + k) < qpos;
;             float sp = fmaxf(z, 0.f) + __builtin_amdgcn_logf(1.f + __builtin_amdgcn_exp2f(-fabsf(z)));
;             run += valid ? -sp : 0.f;
;             e[k] = z + run;
;           }
;           s4[c] = make_float4(e[0], e[1], e[2], e[3]);
;         }
.LBB0_1166:
	s_or_b64 exec, exec, s[44:45]
	s_add_i32 s16, s80, 1
	s_min_i32 s44, s16, s78
	s_sub_i32 s44, s78, s44
	s_lshl_b32 s44, s44, 6
	s_ashr_i32 s45, s44, 31
	s_add_u32 s44, s44, s77
	s_addc_u32 s45, s45, 0
	s_waitcnt lgkmcnt(0)
	s_barrier
	ds_write_b16 v171, v96
	ds_write_b16_d16_hi v171, v96 offset:64
	ds_write_b16 v171, v97 offset:128
	ds_write_b16_d16_hi v171, v97 offset:192
	ds_write_b16 v171, v98 offset:256
	ds_write_b16_d16_hi v171, v98 offset:320
	ds_write_b16 v171, v99 offset:384
	ds_write_b16_d16_hi v171, v99 offset:448
	ds_write_b16 v171, v100 offset:2048
	ds_write_b16_d16_hi v171, v100 offset:2112
	ds_write_b16 v171, v101 offset:2176
	ds_write_b16_d16_hi v171, v101 offset:2240
	ds_write_b16 v171, v102 offset:2304
	ds_write_b16_d16_hi v171, v102 offset:2368
	ds_write_b16 v171, v103 offset:2432
	ds_write_b16_d16_hi v171, v103 offset:2496
	s_waitcnt vmcnt(1)
	ds_write_b16 v171, v108 offset:4096
	ds_write_b16_d16_hi v171, v108 offset:4160
	ds_write_b16 v171, v109 offset:4224
	ds_write_b16_d16_hi v171, v109 offset:4288
	ds_write_b16 v171, v110 offset:4352
	ds_write_b16_d16_hi v171, v110 offset:4416
	ds_write_b16 v171, v111 offset:4480
	ds_write_b16_d16_hi v171, v111 offset:4544
	s_waitcnt vmcnt(0)
	ds_write_b16 v171, v104 offset:6144
	ds_write_b16_d16_hi v171, v104 offset:6208
	ds_write_b16 v171, v105 offset:6272
	ds_write_b16_d16_hi v171, v105 offset:6336
	ds_write_b16 v171, v106 offset:6400
	ds_write_b16_d16_hi v171, v106 offset:6464
	ds_write_b16 v171, v107 offset:6528
	ds_write_b16_d16_hi v171, v107 offset:6592
	v_lshl_add_u64 v[96:97], s[44:45], 0, v[134:135]
	v_mad_u64_u32 v[104:105], s[46:47], v96, s39, v[140:141]
	v_or_b32_e32 v96, s44, v132
	v_mad_i32_i24 v105, v97, s39, v105
	v_mad_u64_u32 v[106:107], s[46:47], v96, s39, v[142:143]
	v_add_co_u32_e32 v96, vcc, s64, v104
	v_mad_i32_i24 v107, s45, v160, v107
	s_nop 0
	v_addc_co_u32_e32 v97, vcc, 0, v105, vcc
	v_add_co_u32_e32 v98, vcc, 0x4c000, v104
	s_nop 1
	v_addc_co_u32_e32 v99, vcc, 0, v105, vcc
	v_add_co_u32_e32 v100, vcc, 0x72000, v104
	global_load_dwordx4 v[120:123], v[96:97], off
	global_load_dwordx4 v[116:119], v[98:99], off
	v_addc_co_u32_e32 v101, vcc, 0, v105, vcc
	global_load_dwordx4 v[96:99], v[106:107], off
	global_load_dwordx4 v[124:127], v[100:101], off
	s_nop 0
	global_load_dwordx4 v[100:103], v[106:107], off offset:64
	global_load_dwordx4 v[108:111], v[106:107], off offset:128
	global_load_dwordx4 v[112:115], v[104:105], off
	s_nop 0
	global_load_dwordx4 v[104:107], v[106:107], off offset:192
	s_and_saveexec_b64 s[44:45], s[10:11]
	s_cbranch_execz .LBB0_1177
	v_mov_b32_e32 v146, 0
	s_mov_b32 s46, 0
	v_mov_b32_e32 v148, v166
	ds_read_b128 v[208:211], v167 offset:112
	ds_read_b128 v[204:207], v167 offset:96
	ds_read_b128 v[200:203], v167 offset:80
	ds_read_b128 v[196:199], v167 offset:64
	ds_read_b128 v[192:195], v167 offset:48
	ds_read_b128 v[188:191], v167 offset:32
	ds_read_b128 v[184:187], v167 offset:16
	ds_read_b128 v[180:183], v167
	v_sub_u32_e32 v212, v144, v173
	v_add_u32_e32 v212, 0xffffc040, v212
	s_waitcnt lgkmcnt(7)
	v_exp_f32_e64 v213, -|v211|
	v_exp_f32_e64 v214, -|v210|
	v_exp_f32_e64 v215, -|v209|
	v_max_f32_e32 v216, 0, v211
	v_max_f32_e32 v217, 0, v210
	v_max_f32_e32 v218, 0, v209
	v_add_f32_e32 v213, 1.0, v213
	v_add_f32_e32 v214, 1.0, v214
	v_add_f32_e32 v215, 1.0, v215
	v_log_f32_e32 v213, v213
	v_log_f32_e32 v214, v214
	v_log_f32_e32 v215, v215
	v_cmp_lt_i32_e32 vcc, 31, v212
	v_cmp_lt_i32_e64 s[92:93], 30, v212
	v_cmp_lt_i32_e64 s[94:95], 29, v212
	v_add_f32_e32 v213, v216, v213
	v_add_f32_e32 v214, v217, v214
	v_add_f32_e32 v215, v218, v215
	v_cndmask_b32_e64 v213, 0, -v213, vcc
	v_cndmask_b32_e64 v214, 0, -v214, s[92:93]
	v_cndmask_b32_e64 v215, 0, -v215, s[94:95]
	v_add_f32_e32 v146, v146, v213
	v_add_f32_e32 v211, v211, v146
	v_add_f32_e32 v146, v146, v214
	v_add_f32_e32 v210, v210, v146
	v_add_f32_e32 v146, v146, v215
	v_add_f32_e32 v209, v209, v146
	s_waitcnt lgkmcnt(6)
	v_exp_f32_e64 v213, -|v208|
	v_exp_f32_e64 v214, -|v207|
	v_exp_f32_e64 v215, -|v206|
	v_max_f32_e32 v216, 0, v208
	v_max_f32_e32 v217, 0, v207
	v_max_f32_e32 v218, 0, v206
	v_add_f32_e32 v213, 1.0, v213
	v_add_f32_e32 v214, 1.0, v214
	v_add_f32_e32 v215, 1.0, v215
	v_log_f32_e32 v213, v213
	v_log_f32_e32 v214, v214
	v_log_f32_e32 v215, v215
	v_cmp_lt_i32_e32 vcc, 28, v212
	v_cmp_lt_i32_e64 s[92:93], 27, v212
	v_cmp_lt_i32_e64 s[94:95], 26, v212
	v_add_f32_e32 v213, v216, v213
	v_add_f32_e32 v214, v217, v214
	v_add_f32_e32 v215, v218, v215
	v_cndmask_b32_e64 v213, 0, -v213, vcc
	v_cndmask_b32_e64 v214, 0, -v214, s[92:93]
	v_cndmask_b32_e64 v215, 0, -v215, s[94:95]
	v_add_f32_e32 v146, v146, v213
	v_add_f32_e32 v208, v208, v146
	v_add_f32_e32 v146, v146, v214
	v_add_f32_e32 v207, v207, v146
	v_add_f32_e32 v146, v146, v215
	v_add_f32_e32 v206, v206, v146
	s_waitcnt lgkmcnt(5)
; template <int DH, int MODE>
; __device__ void attn_item(const Params& p, int layer, int b, int blk, int head, char* smem) {
;     ...
; #pragma unroll 2
;         for (int c = 7; c >= 0; --c) {
;           float4 v = s4[c];
;           float e[4] = {v.x, v.y, v.z, v.w};
; #pragma unroll
;           for (int k = 3; k >= 0; --k) {
;             float z = e[k];
;             bool valid = (kpb + c * 4 + k) < qpos;
;             float sp = fmaxf(z, 0.f) + __builtin_amdgcn_logf(1.f + __builtin_amdgcn_exp2f(-fabsf(z)));
;             run += valid ? -sp : 0.f;
;             e[k] = z + run;
;           }
;           s4[c] = make_float4(e[0], e[1], e[2], e[3]);
;         }
	v_exp_f32_e64 v213, -|v205|
	v_exp_f32_e64 v214, -|v204|
	v_exp_f32_e64 v215, -|v203|
	v_max_f32_e32 v216, 0, v205
	v_max_f32_e32 v217, 0, v204
	v_max_f32_e32 v218, 0, v203
	v_add_f32_e32 v213, 1.0, v213
	v_add_f32_e32 v214, 1.0, v214
	v_add_f32_e32 v215, 1.0, v215
	v_log_f32_e32 v213, v213
	v_log_f32_e32 v214, v214
	v_log_f32_e32 v215, v215
	v_cmp_lt_i32_e32 vcc, 25, v212
	v_cmp_lt_i32_e64 s[92:93], 24, v212
	v_cmp_lt_i32_e64 s[94:95], 23, v212
	v_add_f32_e32 v213, v216, v213
	v_add_f32_e32 v214, v217, v214
	v_add_f32_e32 v215, v218, v215
	v_cndmask_b32_e64 v213, 0, -v213, vcc
	v_cndmask_b32_e64 v214, 0, -v214, s[92:93]
	v_cndmask_b32_e64 v215, 0, -v215, s[94:95]
	v_add_f32_e32 v146, v146, v213
	v_add_f32_e32 v205, v205, v146
	v_add_f32_e32 v146, v146, v214
	v_add_f32_e32 v204, v204, v146
	v_add_f32_e32 v146, v146, v215
	v_add_f32_e32 v203, v203, v146
	v_exp_f32_e64 v213, -|v202|
	v_exp_f32_e64 v214, -|v201|
	v_exp_f32_e64 v215, -|v200|
	v_max_f32_e32 v216, 0, v202
	v_max_f32_e32 v217, 0, v201
	v_max_f32_e32 v218, 0, v200
	v_add_f32_e32 v213, 1.0, v213
	v_add_f32_e32 v214, 1.0, v214
	v_add_f32_e32 v215, 1.0, v215
	v_log_f32_e32 v213, v213
	v_log_f32_e32 v214, v214
	v_log_f32_e32 v215, v215
	v_cmp_lt_i32_e32 vcc, 22, v212
	v_cmp_lt_i32_e64 s[92:93], 21, v212
	v_cmp_lt_i32_e64 s[94:95], 20, v212
	v_add_f32_e32 v213, v216, v213
	v_add_f32_e32 v214, v217, v214
	v_add_f32_e32 v215, v218, v215
	v_cndmask_b32_e64 v213, 0, -v213, vcc
	v_cndmask_b32_e64 v214, 0, -v214, s[92:93]
	v_cndmask_b32_e64 v215, 0, -v215, s[94:95]
	v_add_f32_e32 v146, v146, v213
	v_add_f32_e32 v202, v202, v146
	v_add_f32_e32 v146, v146, v214
	v_add_f32_e32 v201, v201, v146
	v_add_f32_e32 v146, v146, v215
	v_add_f32_e32 v200, v200, v146
	s_waitcnt lgkmcnt(4)
	v_exp_f32_e64 v213, -|v199|
	v_exp_f32_e64 v214, -|v198|
	v_exp_f32_e64 v215, -|v197|
	v_max_f32_e32 v216, 0, v199
	v_max_f32_e32 v217, 0, v198
	v_max_f32_e32 v218, 0, v197
	v_add_f32_e32 v213, 1.0, v213
	v_add_f32_e32 v214, 1.0, v214
	v_add_f32_e32 v215, 1.0, v215
	v_log_f32_e32 v213, v213
	v_log_f32_e32 v214, v214
	v_log_f32_e32 v215, v215
	v_cmp_lt_i32_e32 vcc, 19, v212
	v_cmp_lt_i32_e64 s[92:93], 18, v212
	v_cmp_lt_i32_e64 s[94:95], 17, v212
	v_add_f32_e32 v213, v216, v213
	v_add_f32_e32 v214, v217, v214
	v_add_f32_e32 v215, v218, v215
	v_cndmask_b32_e64 v213, 0, -v213, vcc
	v_cndmask_b32_e64 v214, 0, -v214, s[92:93]
	v_cndmask_b32_e64 v215, 0, -v215, s[94:95]
	v_add_f32_e32 v146, v146, v213
	v_add_f32_e32 v199, v199, v146
	v_add_f32_e32 v146, v146, v214
	v_add_f32_e32 v198, v198, v146
	v_add_f32_e32 v146, v146, v215
	v_add_f32_e32 v197, v197, v146
	s_waitcnt lgkmcnt(3)
	v_exp_f32_e64 v213, -|v196|
	v_exp_f32_e64 v214, -|v195|
	v_exp_f32_e64 v215, -|v194|
	v_max_f32_e32 v216, 0, v196
	v_max_f32_e32 v217, 0, v195
	v_max_f32_e32 v218, 0, v194
	v_add_f32_e32 v213, 1.0, v213
	v_add_f32_e32 v214, 1.0, v214
	v_add_f32_e32 v215, 1.0, v215
	v_log_f32_e32 v213, v213
	v_log_f32_e32 v214, v214
	v_log_f32_e32 v215, v215
	v_cmp_lt_i32_e32 vcc, 16, v212
	v_cmp_lt_i32_e64 s[92:93], 15, v212
	v_cmp_lt_i32_e64 s[94:95], 14, v212
	v_add_f32_e32 v213, v216, v213
	v_add_f32_e32 v214, v217, v214
	v_add_f32_e32 v215, v218, v215
	v_cndmask_b32_e64 v213, 0, -v213, vcc
	v_cndmask_b32_e64 v214, 0, -v214, s[92:93]
	v_cndmask_b32_e64 v215, 0, -v215, s[94:95]
	v_add_f32_e32 v146, v146, v213
	v_add_f32_e32 v196, v196, v146
	v_add_f32_e32 v146, v146, v214
	v_add_f32_e32 v195, v195, v146
	v_add_f32_e32 v146, v146, v215
	v_add_f32_e32 v194, v194, v146
	s_waitcnt lgkmcnt(2)
	v_exp_f32_e64 v213, -|v193|
	v_exp_f32_e64 v214, -|v192|
	v_exp_f32_e64 v215, -|v191|
	v_max_f32_e32 v216, 0, v193
	v_max_f32_e32 v217, 0, v192
	v_max_f32_e32 v218, 0, v191
	v_add_f32_e32 v213, 1.0, v213
	v_add_f32_e32 v214, 1.0, v214
	v_add_f32_e32 v215, 1.0, v215
	v_log_f32_e32 v213, v213
	v_log_f32_e32 v214, v214
	v_log_f32_e32 v215, v215
	v_cmp_lt_i32_e32 vcc, 13, v212
	v_cmp_lt_i32_e64 s[92:93], 12, v212
	v_cmp_lt_i32_e64 s[94:95], 11, v212
	v_add_f32_e32 v213, v216, v213
	v_add_f32_e32 v214, v217, v214
	v_add_f32_e32 v215, v218, v215
	v_cndmask_b32_e64 v213, 0, -v213, vcc
	v_cndmask_b32_e64 v214, 0, -v214, s[92:93]
	v_cndmask_b32_e64 v215, 0, -v215, s[94:95]
	v_add_f32_e32 v146, v146, v213
	v_add_f32_e32 v193, v193, v146
	v_add_f32_e32 v146, v146, v214
	v_add_f32_e32 v192, v192, v146
	v_add_f32_e32 v146, v146, v215
	v_add_f32_e32 v191, v191, v146
	v_exp_f32_e64 v213, -|v190|
	v_exp_f32_e64 v214, -|v189|
	v_exp_f32_e64 v215, -|v188|
	v_max_f32_e32 v216, 0, v190
	v_max_f32_e32 v217, 0, v189
	v_max_f32_e32 v218, 0, v188
	v_add_f32_e32 v213, 1.0, v213
	v_add_f32_e32 v214, 1.0, v214
	v_add_f32_e32 v215, 1.0, v215
	v_log_f32_e32 v213, v213
	v_log_f32_e32 v214, v214
	v_log_f32_e32 v215, v215
	v_cmp_lt_i32_e32 vcc, 10, v212
	v_cmp_lt_i32_e64 s[92:93], 9, v212
	v_cmp_lt_i32_e64 s[94:95], 8, v212
	v_add_f32_e32 v213, v216, v213
	v_add_f32_e32 v214, v217, v214
	v_add_f32_e32 v215, v218, v215
	v_cndmask_b32_e64 v213, 0, -v213, vcc
	v_cndmask_b32_e64 v214, 0, -v214, s[92:93]
	v_cndmask_b32_e64 v215, 0, -v215, s[94:95]
	v_add_f32_e32 v146, v146, v213
	v_add_f32_e32 v190, v190, v146
	v_add_f32_e32 v146, v146, v214
	v_add_f32_e32 v189, v189, v146
	v_add_f32_e32 v146, v146, v215
	v_add_f32_e32 v188, v188, v146
	s_waitcnt lgkmcnt(1)
; __device__ __forceinline__ unsigned pack2(float a, float b) { return (unsigned)f2bf(a) | ((unsigned)f2bf(b) << 16); }
; template <int DH, int MODE>
; __device__ void attn_item(const Params& p, int layer, int b, int blk, int head, char* smem) {
;     ...
; #pragma unroll 2
;         for (int c = 7; c >= 0; --c) {
;           float4 v = s4[c];
;           float e[4] = {v.x, v.y, v.z, v.w};
; #pragma unroll
;           for (int k = 3; k >= 0; --k) {
;             float z = e[k];
;             bool valid = (kpb + c * 4 + k) < qpos;
;             float sp = fmaxf(z, 0.f) + __builtin_amdgcn_logf(1.f + __builtin_amdgcn_exp2f(-fabsf(z)));
;             run += valid ? -sp : 0.f;
;             e[k] = z + run;
;           }
;           s4[c] = make_float4(e[0], e[1], e[2], e[3]);
;         }
;         float other = __shfl_xor(run, 1);
;         float offs = m_run + (half == 0 ? other : 0.f);
; #pragma unroll 2
;         for (int s8 = 0; s8 < 4; ++s8) {
;           float4 va = s4[2 * s8], vb = s4[2 * s8 + 1];
;           float e[8] = {va.x, va.y, va.z, va.w, vb.x, vb.y, vb.z, vb.w};
;           float pv[8];
; #pragma unroll
;           for (int k = 0; k < 8; ++k) {
;             bool valid = (kpb + s8 * 8 + k) < qpos;
;             pv[k] = valid ? __builtin_amdgcn_exp2f(e[k] + offs) : 0.f;
;           }
;           uint4 ov;
;           ov.x = pack2(pv[0], pv[1]); ov.y = pack2(pv[2], pv[3]);
;           ov.z = pack2(pv[4], pv[5]); ov.w = pack2(pv[6], pv[7]);
;           *reinterpret_cast<uint4*>(prow + s8 * 16) = ov;
;         }
	v_exp_f32_e64 v213, -|v187|
	v_exp_f32_e64 v214, -|v186|
	v_exp_f32_e64 v215, -|v185|
	v_max_f32_e32 v216, 0, v187
	v_max_f32_e32 v217, 0, v186
	v_max_f32_e32 v218, 0, v185
	v_add_f32_e32 v213, 1.0, v213
	v_add_f32_e32 v214, 1.0, v214
	v_add_f32_e32 v215, 1.0, v215
	v_log_f32_e32 v213, v213
	v_log_f32_e32 v214, v214
	v_log_f32_e32 v215, v215
	v_cmp_lt_i32_e32 vcc, 7, v212
	v_cmp_lt_i32_e64 s[92:93], 6, v212
	v_cmp_lt_i32_e64 s[94:95], 5, v212
	v_add_f32_e32 v213, v216, v213
	v_add_f32_e32 v214, v217, v214
	v_add_f32_e32 v215, v218, v215
	v_cndmask_b32_e64 v213, 0, -v213, vcc
	v_cndmask_b32_e64 v214, 0, -v214, s[92:93]
	v_cndmask_b32_e64 v215, 0, -v215, s[94:95]
	v_add_f32_e32 v146, v146, v213
	v_add_f32_e32 v187, v187, v146
	v_add_f32_e32 v146, v146, v214
	v_add_f32_e32 v186, v186, v146
	v_add_f32_e32 v146, v146, v215
	v_add_f32_e32 v185, v185, v146
	s_waitcnt lgkmcnt(0)
	v_exp_f32_e64 v213, -|v184|
	v_exp_f32_e64 v214, -|v183|
	v_exp_f32_e64 v215, -|v182|
	v_max_f32_e32 v216, 0, v184
	v_max_f32_e32 v217, 0, v183
	v_max_f32_e32 v218, 0, v182
	v_add_f32_e32 v213, 1.0, v213
	v_add_f32_e32 v214, 1.0, v214
	v_add_f32_e32 v215, 1.0, v215
	v_log_f32_e32 v213, v213
	v_log_f32_e32 v214, v214
	v_log_f32_e32 v215, v215
	v_cmp_lt_i32_e32 vcc, 4, v212
	v_cmp_lt_i32_e64 s[92:93], 3, v212
	v_cmp_lt_i32_e64 s[94:95], 2, v212
	v_add_f32_e32 v213, v216, v213
	v_add_f32_e32 v214, v217, v214
	v_add_f32_e32 v215, v218, v215
	v_cndmask_b32_e64 v213, 0, -v213, vcc
	v_cndmask_b32_e64 v214, 0, -v214, s[92:93]
	v_cndmask_b32_e64 v215, 0, -v215, s[94:95]
	v_add_f32_e32 v146, v146, v213
	v_add_f32_e32 v184, v184, v146
	v_add_f32_e32 v146, v146, v214
	v_add_f32_e32 v183, v183, v146
	v_add_f32_e32 v146, v146, v215
	v_add_f32_e32 v182, v182, v146
	v_exp_f32_e64 v213, -|v181|
	v_exp_f32_e64 v214, -|v180|
	v_max_f32_e32 v216, 0, v181
	v_max_f32_e32 v217, 0, v180
	v_add_f32_e32 v213, 1.0, v213
	v_add_f32_e32 v214, 1.0, v214
	v_log_f32_e32 v213, v213
	v_log_f32_e32 v214, v214
	v_cmp_lt_i32_e32 vcc, 1, v212
	v_cmp_lt_i32_e64 s[92:93], 0, v212
	s_nop 0
	v_add_f32_e32 v213, v216, v213
	v_add_f32_e32 v214, v217, v214
	v_cndmask_b32_e64 v213, 0, -v213, vcc
	v_cndmask_b32_e64 v214, 0, -v214, s[92:93]
	v_add_f32_e32 v146, v146, v213
	v_add_f32_e32 v181, v181, v146
	v_add_f32_e32 v146, v146, v214
	v_add_f32_e32 v180, v180, v146
	ds_write_b128 v167, v[180:183]
	ds_write_b128 v167, v[184:187] offset:16
	ds_write_b128 v167, v[188:191] offset:32
	ds_write_b128 v167, v[192:195] offset:48
	ds_write_b128 v167, v[196:199] offset:64
	ds_write_b128 v167, v[200:203] offset:80
	ds_write_b128 v167, v[204:207] offset:96
	ds_write_b128 v167, v[208:211] offset:112
	ds_bpermute_b32 v147, v163, v146
	s_mov_b32 s81, 0
	v_mov_b32_e32 v175, v168
	v_mov_b32_e32 v177, v167
	s_waitcnt lgkmcnt(0)
	v_cndmask_b32_e64 v148, 0, v147, s[8:9]
	v_add_f32_e32 v176, v174, v148
	ds_read_b128 v[180:183], v177
	ds_read_b128 v[184:187], v177 offset:16
	ds_read_b128 v[188:191], v177 offset:32
	ds_read_b128 v[192:195], v177 offset:48
	ds_read_b128 v[196:199], v177 offset:64
	ds_read_b128 v[200:203], v177 offset:80
	ds_read_b128 v[204:207], v177 offset:96
	ds_read_b128 v[208:211], v177 offset:112
	v_sub_u32_e32 v212, v144, v173
	v_add_u32_e32 v212, 0xffffc040, v212
	s_waitcnt lgkmcnt(7)
	v_add_f32_e32 v180, v176, v180
	v_add_f32_e32 v181, v176, v181
	v_add_f32_e32 v182, v176, v182
	v_exp_f32_e32 v180, v180
	v_exp_f32_e32 v181, v181
	v_exp_f32_e32 v182, v182
	v_cmp_lt_i32_e32 vcc, 0, v212
	v_cmp_lt_i32_e64 s[92:93], 1, v212
	v_cmp_lt_i32_e64 s[94:95], 2, v212
	v_cndmask_b32_e32 v180, 0, v180, vcc
	v_cndmask_b32_e64 v181, 0, v181, s[92:93]
	v_cndmask_b32_e64 v182, 0, v182, s[94:95]
	s_waitcnt lgkmcnt(6)
	v_add_f32_e32 v183, v176, v183
	v_add_f32_e32 v184, v176, v184
	v_add_f32_e32 v185, v176, v185
	v_exp_f32_e32 v183, v183
	v_exp_f32_e32 v184, v184
	v_exp_f32_e32 v185, v185
	v_cmp_lt_i32_e32 vcc, 3, v212
	v_cmp_lt_i32_e64 s[92:93], 4, v212
	v_cmp_lt_i32_e64 s[94:95], 5, v212
	v_cndmask_b32_e32 v183, 0, v183, vcc
	v_cndmask_b32_e64 v184, 0, v184, s[92:93]
	v_cndmask_b32_e64 v185, 0, v185, s[94:95]
	s_waitcnt lgkmcnt(5)
; __device__ __forceinline__ unsigned pack2(float a, float b) { return (unsigned)f2bf(a) | ((unsigned)f2bf(b) << 16); }
; template <int DH, int MODE>
; __device__ void attn_item(const Params& p, int layer, int b, int blk, int head, char* smem) {
;     ...
; #pragma unroll 2
;         for (int s8 = 0; s8 < 4; ++s8) {
;           float4 va = s4[2 * s8], vb = s4[2 * s8 + 1];
;           float e[8] = {va.x, va.y, va.z, va.w, vb.x, vb.y, vb.z, vb.w};
;           float pv[8];
; #pragma unroll
;           for (int k = 0; k < 8; ++k) {
;             bool valid = (kpb + s8 * 8 + k) < qpos;
;             pv[k] = valid ? __builtin_amdgcn_exp2f(e[k] + offs) : 0.f;
;           }
;           uint4 ov;
;           ov.x = pack2(pv[0], pv[1]); ov.y = pack2(pv[2], pv[3]);
;           ov.z = pack2(pv[4], pv[5]); ov.w = pack2(pv[6], pv[7]);
;           *reinterpret_cast<uint4*>(prow + s8 * 16) = ov;
;         }
	v_add_f32_e32 v186, v176, v186
	v_add_f32_e32 v187, v176, v187
	v_add_f32_e32 v188, v176, v188
	v_exp_f32_e32 v186, v186
	v_exp_f32_e32 v187, v187
	v_exp_f32_e32 v188, v188
	v_cmp_lt_i32_e32 vcc, 6, v212
	v_cmp_lt_i32_e64 s[92:93], 7, v212
	v_cmp_lt_i32_e64 s[94:95], 8, v212
	v_cndmask_b32_e32 v186, 0, v186, vcc
	v_cndmask_b32_e64 v187, 0, v187, s[92:93]
	v_cndmask_b32_e64 v188, 0, v188, s[94:95]
	v_add_f32_e32 v189, v176, v189
	v_add_f32_e32 v190, v176, v190
	v_add_f32_e32 v191, v176, v191
	v_exp_f32_e32 v189, v189
	v_exp_f32_e32 v190, v190
	v_exp_f32_e32 v191, v191
	v_cmp_lt_i32_e32 vcc, 9, v212
	v_cmp_lt_i32_e64 s[92:93], 10, v212
	v_cmp_lt_i32_e64 s[94:95], 11, v212
	v_cndmask_b32_e32 v189, 0, v189, vcc
	v_cndmask_b32_e64 v190, 0, v190, s[92:93]
	v_cndmask_b32_e64 v191, 0, v191, s[94:95]
	s_waitcnt lgkmcnt(4)
	v_add_f32_e32 v192, v176, v192
	v_add_f32_e32 v193, v176, v193
	v_add_f32_e32 v194, v176, v194
	v_exp_f32_e32 v192, v192
	v_exp_f32_e32 v193, v193
	v_exp_f32_e32 v194, v194
	v_cmp_lt_i32_e32 vcc, 12, v212
	v_cmp_lt_i32_e64 s[92:93], 13, v212
	v_cmp_lt_i32_e64 s[94:95], 14, v212
	v_cndmask_b32_e32 v192, 0, v192, vcc
	v_cndmask_b32_e64 v193, 0, v193, s[92:93]
	v_cndmask_b32_e64 v194, 0, v194, s[94:95]
	s_waitcnt lgkmcnt(3)
	v_add_f32_e32 v195, v176, v195
	v_add_f32_e32 v196, v176, v196
	v_add_f32_e32 v197, v176, v197
	v_exp_f32_e32 v195, v195
	v_exp_f32_e32 v196, v196
	v_exp_f32_e32 v197, v197
	v_cmp_lt_i32_e32 vcc, 15, v212
	v_cmp_lt_i32_e64 s[92:93], 16, v212
	v_cmp_lt_i32_e64 s[94:95], 17, v212
	v_cndmask_b32_e32 v195, 0, v195, vcc
	v_cndmask_b32_e64 v196, 0, v196, s[92:93]
	v_cndmask_b32_e64 v197, 0, v197, s[94:95]
	s_waitcnt lgkmcnt(2)
	v_add_f32_e32 v198, v176, v198
	v_add_f32_e32 v199, v176, v199
	v_add_f32_e32 v200, v176, v200
	v_exp_f32_e32 v198, v198
	v_exp_f32_e32 v199, v199
	v_exp_f32_e32 v200, v200
	v_cmp_lt_i32_e32 vcc, 18, v212
	v_cmp_lt_i32_e64 s[92:93], 19, v212
	v_cmp_lt_i32_e64 s[94:95], 20, v212
	v_cndmask_b32_e32 v198, 0, v198, vcc
	v_cndmask_b32_e64 v199, 0, v199, s[92:93]
	v_cndmask_b32_e64 v200, 0, v200, s[94:95]
	v_add_f32_e32 v201, v176, v201
	v_add_f32_e32 v202, v176, v202
	v_add_f32_e32 v203, v176, v203
	v_exp_f32_e32 v201, v201
	v_exp_f32_e32 v202, v202
	v_exp_f32_e32 v203, v203
	v_cmp_lt_i32_e32 vcc, 21, v212
	v_cmp_lt_i32_e64 s[92:93], 22, v212
	v_cmp_lt_i32_e64 s[94:95], 23, v212
	v_cndmask_b32_e32 v201, 0, v201, vcc
	v_cndmask_b32_e64 v202, 0, v202, s[92:93]
	v_cndmask_b32_e64 v203, 0, v203, s[94:95]
	s_waitcnt lgkmcnt(1)
	v_add_f32_e32 v204, v176, v204
	v_add_f32_e32 v205, v176, v205
	v_add_f32_e32 v206, v176, v206
	v_exp_f32_e32 v204, v204
	v_exp_f32_e32 v205, v205
	v_exp_f32_e32 v206, v206
	v_cmp_lt_i32_e32 vcc, 24, v212
	v_cmp_lt_i32_e64 s[92:93], 25, v212
	v_cmp_lt_i32_e64 s[94:95], 26, v212
	v_cndmask_b32_e32 v204, 0, v204, vcc
	v_cndmask_b32_e64 v205, 0, v205, s[92:93]
	v_cndmask_b32_e64 v206, 0, v206, s[94:95]
	s_waitcnt lgkmcnt(0)
	v_add_f32_e32 v207, v176, v207
	v_add_f32_e32 v208, v176, v208
	v_add_f32_e32 v209, v176, v209
	v_exp_f32_e32 v207, v207
	v_exp_f32_e32 v208, v208
	v_exp_f32_e32 v209, v209
	v_cmp_lt_i32_e32 vcc, 27, v212
	v_cmp_lt_i32_e64 s[92:93], 28, v212
	v_cmp_lt_i32_e64 s[94:95], 29, v212
	v_cndmask_b32_e32 v207, 0, v207, vcc
	v_cndmask_b32_e64 v208, 0, v208, s[92:93]
	v_cndmask_b32_e64 v209, 0, v209, s[94:95]
	v_add_f32_e32 v210, v176, v210
	v_add_f32_e32 v211, v176, v211
	v_exp_f32_e32 v210, v210
	v_exp_f32_e32 v211, v211
	v_cmp_lt_i32_e32 vcc, 30, v212
	v_cmp_lt_i32_e64 s[92:93], 31, v212
	s_nop 0
	v_cndmask_b32_e32 v210, 0, v210, vcc
	v_cndmask_b32_e64 v211, 0, v211, s[92:93]
	v_cvt_pk_bf16_f32 v148, v180, v181
	v_cvt_pk_bf16_f32 v149, v182, v183
	v_cvt_pk_bf16_f32 v150, v184, v185
	v_cvt_pk_bf16_f32 v151, v186, v187
	ds_write_b128 v175, v[148:151]
	s_nop 0
	v_cvt_pk_bf16_f32 v148, v188, v189
	v_cvt_pk_bf16_f32 v149, v190, v191
	v_cvt_pk_bf16_f32 v150, v192, v193
	v_cvt_pk_bf16_f32 v151, v194, v195
	ds_write_b128 v175, v[148:151] offset:16
	s_nop 0
	v_cvt_pk_bf16_f32 v148, v196, v197
	v_cvt_pk_bf16_f32 v149, v198, v199
	v_cvt_pk_bf16_f32 v150, v200, v201
	v_cvt_pk_bf16_f32 v151, v202, v203
	ds_write_b128 v175, v[148:151] offset:32
	s_nop 0
	v_cvt_pk_bf16_f32 v148, v204, v205
	v_cvt_pk_bf16_f32 v149, v206, v207
	v_cvt_pk_bf16_f32 v150, v208, v209
	v_cvt_pk_bf16_f32 v151, v210, v211
	ds_write_b128 v175, v[148:151] offset:48
	s_branch .LBB0_1176
